# GEMM K-loops (up A/B, down A/B, in-proj): first iteration peeled with srcC=0 MFMAs, accumulator zeroing removed
# speedup vs baseline: 1.0047x; 1.0007x over previous
.LBB0_209:
	s_ashr_i32 s11, s10, 31
	s_lshl_b64 s[18:19], s[10:11], 19
	s_add_u32 s18, s40, s18
	s_addc_u32 s19, s41, s19
	s_and_b64 s[24:25], s[44:45], exec
	s_cselect_b32 s11, s19, s21
	s_cselect_b32 s59, s18, s20
	s_ashr_i32 s15, s14, 31
	s_lshl_b64 s[24:25], s[14:15], 19
	s_add_u32 s36, s34, s24
	s_addc_u32 s37, s35, s25
	s_and_b64 s[24:25], s[44:45], exec
	s_cselect_b32 s15, s37, s23
	s_cselect_b32 s60, s36, s22
	s_add_u32 s20, s20, 0x40080
	s_addc_u32 s21, s21, 0
	s_add_u32 s61, s22, 0x100
	s_addc_u32 s64, s23, 0
	s_mov_b32 s65, -2
	s_add_u32 s22, s20, 0xfffc0080
	s_addc_u32 s23, s21, -1
	s_add_i32 s70, 0, 0x10000
	s_cmp_eq_u32 s65, 12
	s_cselect_b32 s25, s11, s23
	s_cselect_b32 s24, s59, s22
	v_add_u32_e32 v140, s70, v143
	s_cselect_b32 s23, s15, s64
	s_cselect_b32 s22, s60, s61
	s_add_i32 s87, 0, 0x14000
	ds_read_b128 v[146:149], v140
	ds_read_b128 v[150:153], v140 offset:1024
	ds_read_b128 v[154:157], v140 offset:2048
	ds_read_b128 v[158:161], v140 offset:3072
	v_add_u32_e32 v140, s87, v143
	ds_read_b128 v[162:165], v140
	ds_read_b128 v[166:169], v140 offset:1024
	ds_read_b128 v[170:173], v140 offset:2048
	ds_read_b128 v[174:177], v140 offset:3072
	v_lshl_add_u64 v[140:141], s[20:21], 0, v[136:137]
	s_add_i32 m0, s42, 0xc000
	ds_read_b128 v[178:181], v145
	ds_read_b128 v[182:185], v145 offset:1024
	ds_read_b128 v[186:189], v145 offset:2048
	ds_read_b128 v[190:193], v145 offset:3072
	ds_read_b128 v[194:197], v145 offset:4096
	ds_read_b128 v[198:201], v145 offset:5120
	ds_read_b128 v[202:205], v145 offset:6144
	ds_read_b128 v[216:219], v145 offset:7168
	global_load_lds_dwordx4 v[140:141], off
	v_lshl_add_u64 v[140:141], s[20:21], 0, v[138:139]
	s_add_i32 m0, s42, 0xe000
	s_nop 0
	global_load_lds_dwordx4 v[140:141], off
	s_waitcnt vmcnt(8)
	s_waitcnt lgkmcnt(0)
	s_barrier
	s_setprio 1
	s_waitcnt lgkmcnt(0)
	v_mfma_f32_16x16x32_bf16 v[126:129], v[146:149], v[178:181], 0
	v_mfma_f32_16x16x32_bf16 v[118:121], v[154:157], v[178:181], 0
	v_mfma_f32_16x16x32_bf16 v[110:113], v[146:149], v[186:189], 0
	v_mfma_f32_16x16x32_bf16 v[102:105], v[154:157], v[186:189], 0
	v_mfma_f32_16x16x32_bf16 v[94:97], v[146:149], v[194:197], 0
	v_mfma_f32_16x16x32_bf16 v[86:89], v[154:157], v[194:197], 0
	v_mfma_f32_16x16x32_bf16 v[78:81], v[146:149], v[202:205], 0
	v_mfma_f32_16x16x32_bf16 v[70:73], v[154:157], v[202:205], 0
	v_mfma_f32_16x16x32_bf16 v[126:129], v[150:153], v[182:185], v[126:129]
	v_mfma_f32_16x16x32_bf16 v[118:121], v[158:161], v[182:185], v[118:121]
	v_mfma_f32_16x16x32_bf16 v[110:113], v[150:153], v[190:193], v[110:113]
	v_mfma_f32_16x16x32_bf16 v[102:105], v[158:161], v[190:193], v[102:105]
	v_mfma_f32_16x16x32_bf16 v[94:97], v[150:153], v[198:201], v[94:97]
	v_mfma_f32_16x16x32_bf16 v[86:89], v[158:161], v[198:201], v[86:89]
	v_mfma_f32_16x16x32_bf16 v[78:81], v[150:153], v[216:219], v[78:81]
	v_mfma_f32_16x16x32_bf16 v[70:73], v[158:161], v[216:219], v[70:73]
	s_setprio 0
	s_setprio 1
	v_mfma_f32_16x16x32_bf16 v[122:125], v[162:165], v[178:181], 0
	v_mfma_f32_16x16x32_bf16 v[114:117], v[170:173], v[178:181], 0
	v_mfma_f32_16x16x32_bf16 v[106:109], v[162:165], v[186:189], 0
	v_mfma_f32_16x16x32_bf16 v[98:101], v[170:173], v[186:189], 0
	v_mfma_f32_16x16x32_bf16 v[90:93], v[162:165], v[194:197], 0
	v_mfma_f32_16x16x32_bf16 v[82:85], v[170:173], v[194:197], 0
	v_mfma_f32_16x16x32_bf16 v[74:77], v[162:165], v[202:205], 0
	v_mfma_f32_16x16x32_bf16 v[66:69], v[170:173], v[202:205], 0
	v_mfma_f32_16x16x32_bf16 v[122:125], v[166:169], v[182:185], v[122:125]
	v_mfma_f32_16x16x32_bf16 v[114:117], v[174:177], v[182:185], v[114:117]
	v_mfma_f32_16x16x32_bf16 v[106:109], v[166:169], v[190:193], v[106:109]
	v_mfma_f32_16x16x32_bf16 v[98:101], v[174:177], v[190:193], v[98:101]
	v_mfma_f32_16x16x32_bf16 v[90:93], v[166:169], v[198:201], v[90:93]
	v_mfma_f32_16x16x32_bf16 v[82:85], v[174:177], v[198:201], v[82:85]
	v_mfma_f32_16x16x32_bf16 v[74:77], v[166:169], v[216:219], v[74:77]
	v_mfma_f32_16x16x32_bf16 v[66:69], v[174:177], v[216:219], v[66:69]
	s_setprio 0
	s_barrier
	s_add_i32 s70, s70, s12
	v_lshl_add_u64 v[140:141], s[22:23], 0, v[0:1]
	s_mov_b32 m0, s70
	ds_read_b128 v[178:181], v145 offset:16384
	ds_read_b128 v[182:185], v145 offset:17408
	ds_read_b128 v[186:189], v145 offset:18432
	ds_read_b128 v[190:193], v145 offset:19456
	ds_read_b128 v[194:197], v145 offset:20480
	ds_read_b128 v[198:201], v145 offset:21504
	ds_read_b128 v[202:205], v145 offset:22528
	ds_read_b128 v[216:219], v145 offset:23552
	global_load_lds_dwordx4 v[140:141], off
	s_add_i32 m0, s70, 0x2000
	s_add_u32 s76, s22, 0x40000
	v_lshl_add_u64 v[220:221], s[22:23], 0, v[134:135]
	s_addc_u32 s77, s23, 0
	s_add_i32 s70, s87, s12
	global_load_lds_dwordx4 v[220:221], off
	v_lshl_add_u64 v[222:223], s[76:77], 0, v[0:1]
	s_mov_b32 m0, s70
	v_lshl_add_u64 v[224:225], s[24:25], 0, v[132:133]
	global_load_lds_dwordx4 v[222:223], off
	v_lshl_add_u64 v[222:223], s[76:77], 0, v[134:135]
	s_add_i32 m0, s70, 0x2000
	s_nop 0
	global_load_lds_dwordx4 v[222:223], off
	v_lshl_add_u64 v[222:223], s[24:25], 0, v[130:131]
	s_mov_b32 m0, s42
	s_nop 0
	global_load_lds_dwordx4 v[222:223], off
	s_mov_b32 m0, s43
	s_nop 0
	global_load_lds_dwordx4 v[224:225], off
	s_waitcnt vmcnt(8)
	s_waitcnt lgkmcnt(0)
	s_barrier
	s_setprio 1
	s_waitcnt lgkmcnt(0)
	v_mfma_f32_16x16x32_bf16 v[62:65], v[146:149], v[178:181], 0
	v_mfma_f32_16x16x32_bf16 v[54:57], v[154:157], v[178:181], 0
	v_mfma_f32_16x16x32_bf16 v[46:49], v[146:149], v[186:189], 0
	v_mfma_f32_16x16x32_bf16 v[38:41], v[154:157], v[186:189], 0
	v_mfma_f32_16x16x32_bf16 v[30:33], v[146:149], v[194:197], 0
	v_mfma_f32_16x16x32_bf16 v[22:25], v[154:157], v[194:197], 0
	v_mfma_f32_16x16x32_bf16 v[14:17], v[146:149], v[202:205], 0
	v_mfma_f32_16x16x32_bf16 v[6:9], v[154:157], v[202:205], 0
	v_mfma_f32_16x16x32_bf16 v[62:65], v[150:153], v[182:185], v[62:65]
	v_mfma_f32_16x16x32_bf16 v[54:57], v[158:161], v[182:185], v[54:57]
	v_mfma_f32_16x16x32_bf16 v[46:49], v[150:153], v[190:193], v[46:49]
	v_mfma_f32_16x16x32_bf16 v[38:41], v[158:161], v[190:193], v[38:41]
	v_mfma_f32_16x16x32_bf16 v[30:33], v[150:153], v[198:201], v[30:33]
	v_mfma_f32_16x16x32_bf16 v[22:25], v[158:161], v[198:201], v[22:25]
	v_mfma_f32_16x16x32_bf16 v[14:17], v[150:153], v[216:219], v[14:17]
	v_mfma_f32_16x16x32_bf16 v[6:9], v[158:161], v[216:219], v[6:9]
	s_setprio 0
	s_setprio 1
	v_mfma_f32_16x16x32_bf16 v[58:61], v[162:165], v[178:181], 0
	v_mfma_f32_16x16x32_bf16 v[50:53], v[170:173], v[178:181], 0
	v_mfma_f32_16x16x32_bf16 v[42:45], v[162:165], v[186:189], 0
	v_mfma_f32_16x16x32_bf16 v[34:37], v[170:173], v[186:189], 0
	v_mfma_f32_16x16x32_bf16 v[26:29], v[162:165], v[194:197], 0
	v_mfma_f32_16x16x32_bf16 v[18:21], v[170:173], v[194:197], 0
	v_mfma_f32_16x16x32_bf16 v[10:13], v[162:165], v[202:205], 0
	v_mfma_f32_16x16x32_bf16 v[2:5], v[170:173], v[202:205], 0
	v_mfma_f32_16x16x32_bf16 v[58:61], v[166:169], v[182:185], v[58:61]
	v_mfma_f32_16x16x32_bf16 v[50:53], v[174:177], v[182:185], v[50:53]
	v_mfma_f32_16x16x32_bf16 v[42:45], v[166:169], v[190:193], v[42:45]
	v_mfma_f32_16x16x32_bf16 v[34:37], v[174:177], v[190:193], v[34:37]
	v_mfma_f32_16x16x32_bf16 v[26:29], v[166:169], v[198:201], v[26:29]
	v_mfma_f32_16x16x32_bf16 v[18:21], v[174:177], v[198:201], v[18:21]
	v_mfma_f32_16x16x32_bf16 v[10:13], v[166:169], v[216:219], v[10:13]
	v_mfma_f32_16x16x32_bf16 v[2:5], v[174:177], v[216:219], v[2:5]
	s_setprio 0
	s_barrier
	s_add_i32 s70, 0, 0x18000
	s_add_i32 s76, 0, 0x1c000
	v_add_u32_e32 v158, s70, v143
	v_add_u32_e32 v174, s76, v143
	ds_read_b128 v[146:149], v158
	ds_read_b128 v[150:153], v158 offset:1024
	ds_read_b128 v[154:157], v158 offset:2048
	ds_read_b128 v[158:161], v158 offset:3072
	ds_read_b128 v[162:165], v174
	ds_read_b128 v[166:169], v174 offset:1024
	ds_read_b128 v[170:173], v174 offset:2048
	ds_read_b128 v[174:177], v174 offset:3072
	s_add_u32 s24, s24, 0x40000
	s_addc_u32 s25, s25, 0
	s_mov_b32 m0, s46
	v_lshl_add_u64 v[228:229], s[24:25], 0, v[130:131]
	ds_read_b128 v[178:181], v145 offset:32768
	ds_read_b128 v[182:185], v145 offset:33792
	ds_read_b128 v[186:189], v145 offset:34816
	ds_read_b128 v[190:193], v145 offset:35840
	ds_read_b128 v[194:197], v145 offset:36864
	ds_read_b128 v[198:201], v145 offset:37888
	ds_read_b128 v[202:205], v145 offset:38912
	ds_read_b128 v[216:219], v145 offset:39936
	global_load_lds_dwordx4 v[228:229], off
	v_lshl_add_u64 v[228:229], s[24:25], 0, v[132:133]
	s_mov_b32 m0, s47
	s_nop 0
	global_load_lds_dwordx4 v[228:229], off
	s_waitcnt vmcnt(8)
	s_waitcnt lgkmcnt(0)
	s_barrier
	s_setprio 1
	s_waitcnt lgkmcnt(0)
	v_mfma_f32_16x16x32_bf16 v[126:129], v[146:149], v[178:181], v[126:129]
	v_mfma_f32_16x16x32_bf16 v[118:121], v[154:157], v[178:181], v[118:121]
	v_mfma_f32_16x16x32_bf16 v[110:113], v[146:149], v[186:189], v[110:113]
	v_mfma_f32_16x16x32_bf16 v[102:105], v[154:157], v[186:189], v[102:105]
	v_mfma_f32_16x16x32_bf16 v[94:97], v[146:149], v[194:197], v[94:97]
	v_mfma_f32_16x16x32_bf16 v[86:89], v[154:157], v[194:197], v[86:89]
	v_mfma_f32_16x16x32_bf16 v[78:81], v[146:149], v[202:205], v[78:81]
	v_mfma_f32_16x16x32_bf16 v[70:73], v[154:157], v[202:205], v[70:73]
	v_mfma_f32_16x16x32_bf16 v[126:129], v[150:153], v[182:185], v[126:129]
	v_mfma_f32_16x16x32_bf16 v[118:121], v[158:161], v[182:185], v[118:121]
	v_mfma_f32_16x16x32_bf16 v[110:113], v[150:153], v[190:193], v[110:113]
	v_mfma_f32_16x16x32_bf16 v[102:105], v[158:161], v[190:193], v[102:105]
	v_mfma_f32_16x16x32_bf16 v[94:97], v[150:153], v[198:201], v[94:97]
	v_mfma_f32_16x16x32_bf16 v[86:89], v[158:161], v[198:201], v[86:89]
	v_mfma_f32_16x16x32_bf16 v[78:81], v[150:153], v[216:219], v[78:81]
	v_mfma_f32_16x16x32_bf16 v[70:73], v[158:161], v[216:219], v[70:73]
	s_setprio 0
	s_setprio 1
	v_mfma_f32_16x16x32_bf16 v[122:125], v[162:165], v[178:181], v[122:125]
	v_mfma_f32_16x16x32_bf16 v[114:117], v[170:173], v[178:181], v[114:117]
	v_mfma_f32_16x16x32_bf16 v[106:109], v[162:165], v[186:189], v[106:109]
	v_mfma_f32_16x16x32_bf16 v[98:101], v[170:173], v[186:189], v[98:101]
	v_mfma_f32_16x16x32_bf16 v[90:93], v[162:165], v[194:197], v[90:93]
	v_mfma_f32_16x16x32_bf16 v[82:85], v[170:173], v[194:197], v[82:85]
	v_mfma_f32_16x16x32_bf16 v[74:77], v[162:165], v[202:205], v[74:77]
	v_mfma_f32_16x16x32_bf16 v[66:69], v[170:173], v[202:205], v[66:69]
	v_mfma_f32_16x16x32_bf16 v[122:125], v[166:169], v[182:185], v[122:125]
	v_mfma_f32_16x16x32_bf16 v[114:117], v[174:177], v[182:185], v[114:117]
	v_mfma_f32_16x16x32_bf16 v[106:109], v[166:169], v[190:193], v[106:109]
	v_mfma_f32_16x16x32_bf16 v[98:101], v[174:177], v[190:193], v[98:101]
	v_mfma_f32_16x16x32_bf16 v[90:93], v[166:169], v[198:201], v[90:93]
	v_mfma_f32_16x16x32_bf16 v[82:85], v[174:177], v[198:201], v[82:85]
	v_mfma_f32_16x16x32_bf16 v[74:77], v[166:169], v[216:219], v[74:77]
	v_mfma_f32_16x16x32_bf16 v[66:69], v[174:177], v[216:219], v[66:69]
	s_setprio 0
	s_barrier
	s_add_i32 s24, s70, s12
	v_lshl_add_u64 v[140:141], v[140:141], 0, s[30:31]
	s_mov_b32 m0, s24
	ds_read_b128 v[178:181], v145 offset:49152
	ds_read_b128 v[182:185], v145 offset:50176
	ds_read_b128 v[186:189], v145 offset:51200
	ds_read_b128 v[190:193], v145 offset:52224
	ds_read_b128 v[194:197], v145 offset:53248
	ds_read_b128 v[198:201], v145 offset:54272
	ds_read_b128 v[202:205], v145 offset:55296
	ds_read_b128 v[216:219], v145 offset:56320
	global_load_lds_dwordx4 v[140:141], off
	s_add_i32 m0, s24, 0x2000
	s_add_u32 s22, s22, 0x40080
	v_lshl_add_u64 v[140:141], v[220:221], 0, s[30:31]
	s_addc_u32 s23, s23, 0
	s_add_i32 s24, s76, s12
	global_load_lds_dwordx4 v[140:141], off
	v_lshl_add_u64 v[140:141], s[22:23], 0, v[0:1]
	s_mov_b32 m0, s24
	s_nop 0
	global_load_lds_dwordx4 v[140:141], off
	v_lshl_add_u64 v[140:141], s[22:23], 0, v[134:135]
	s_add_i32 m0, s24, 0x2000
	s_nop 0
	global_load_lds_dwordx4 v[140:141], off
	v_lshl_add_u64 v[140:141], v[222:223], 0, s[30:31]
	s_mov_b32 m0, s50
	s_nop 0
	global_load_lds_dwordx4 v[140:141], off
	v_lshl_add_u64 v[140:141], v[224:225], 0, s[30:31]
	s_mov_b32 m0, s51
	s_nop 0
	global_load_lds_dwordx4 v[140:141], off
	s_waitcnt vmcnt(8)
	s_waitcnt lgkmcnt(0)
	s_barrier
	s_setprio 1
	s_waitcnt lgkmcnt(0)
	v_mfma_f32_16x16x32_bf16 v[62:65], v[146:149], v[178:181], v[62:65]
	v_mfma_f32_16x16x32_bf16 v[54:57], v[154:157], v[178:181], v[54:57]
	v_mfma_f32_16x16x32_bf16 v[46:49], v[146:149], v[186:189], v[46:49]
	v_mfma_f32_16x16x32_bf16 v[38:41], v[154:157], v[186:189], v[38:41]
	v_mfma_f32_16x16x32_bf16 v[30:33], v[146:149], v[194:197], v[30:33]
	v_mfma_f32_16x16x32_bf16 v[22:25], v[154:157], v[194:197], v[22:25]
	v_mfma_f32_16x16x32_bf16 v[14:17], v[146:149], v[202:205], v[14:17]
	v_mfma_f32_16x16x32_bf16 v[6:9], v[154:157], v[202:205], v[6:9]
	v_mfma_f32_16x16x32_bf16 v[62:65], v[150:153], v[182:185], v[62:65]
	v_mfma_f32_16x16x32_bf16 v[54:57], v[158:161], v[182:185], v[54:57]
	v_mfma_f32_16x16x32_bf16 v[46:49], v[150:153], v[190:193], v[46:49]
	v_mfma_f32_16x16x32_bf16 v[38:41], v[158:161], v[190:193], v[38:41]
	v_mfma_f32_16x16x32_bf16 v[30:33], v[150:153], v[198:201], v[30:33]
	v_mfma_f32_16x16x32_bf16 v[22:25], v[158:161], v[198:201], v[22:25]
	v_mfma_f32_16x16x32_bf16 v[14:17], v[150:153], v[216:219], v[14:17]
	v_mfma_f32_16x16x32_bf16 v[6:9], v[158:161], v[216:219], v[6:9]
	s_setprio 0
	s_setprio 1
	v_mfma_f32_16x16x32_bf16 v[58:61], v[162:165], v[178:181], v[58:61]
	v_mfma_f32_16x16x32_bf16 v[50:53], v[170:173], v[178:181], v[50:53]
	v_mfma_f32_16x16x32_bf16 v[42:45], v[162:165], v[186:189], v[42:45]
	v_mfma_f32_16x16x32_bf16 v[34:37], v[170:173], v[186:189], v[34:37]
	v_mfma_f32_16x16x32_bf16 v[26:29], v[162:165], v[194:197], v[26:29]
	v_mfma_f32_16x16x32_bf16 v[18:21], v[170:173], v[194:197], v[18:21]
	v_mfma_f32_16x16x32_bf16 v[10:13], v[162:165], v[202:205], v[10:13]
	v_mfma_f32_16x16x32_bf16 v[2:5], v[170:173], v[202:205], v[2:5]
	v_mfma_f32_16x16x32_bf16 v[58:61], v[166:169], v[182:185], v[58:61]
	v_mfma_f32_16x16x32_bf16 v[50:53], v[174:177], v[182:185], v[50:53]
	v_mfma_f32_16x16x32_bf16 v[42:45], v[166:169], v[190:193], v[42:45]
	v_mfma_f32_16x16x32_bf16 v[34:37], v[174:177], v[190:193], v[34:37]
	v_mfma_f32_16x16x32_bf16 v[26:29], v[166:169], v[198:201], v[26:29]
	v_mfma_f32_16x16x32_bf16 v[18:21], v[174:177], v[198:201], v[18:21]
	v_mfma_f32_16x16x32_bf16 v[10:13], v[166:169], v[216:219], v[10:13]
	v_mfma_f32_16x16x32_bf16 v[2:5], v[174:177], v[216:219], v[2:5]
	s_setprio 0
	s_barrier
	s_add_i32 s65, s65, 2
	s_add_u32 s20, s20, 0x100
	s_addc_u32 s21, s21, 0
	s_add_u32 s61, s61, 0x100
	s_addc_u32 s64, s64, 0
	s_cmp_gt_u32 s65, 13
	s_cbranch_scc0 .LBB0_210
	s_branch .Lgemm_kexit_0

.Lgemm_kexit_0:
	s_and_b64 vcc, exec, s[16:17]
	s_cbranch_vccz .LBB0_213
	s_barrier

.LBB0_283:
	s_add_u32 s48, s20, 0x100
	s_addc_u32 s49, s21, 0
	s_mov_b32 s65, -2
	s_add_u32 s20, s18, 0x100
	s_addc_u32 s21, s19, 0
	s_add_i32 s70, 0, 0x10000
	s_cmp_eq_u32 s65, 40
	s_cselect_b32 s25, s11, s21
	s_cselect_b32 s24, s10, s20
	s_cselect_b32 s23, s15, s49
	s_cselect_b32 s22, s14, s48
	s_add_i32 s76, 0, 0x14000
	v_add_u32_e32 v152, s70, v145
	v_add_u32_e32 v168, s76, v145
	ds_read_b128 v[136:139], v152
	ds_read_b128 v[140:143], v152 offset:1024
	ds_read_b128 v[148:151], v152 offset:2048
	ds_read_b128 v[152:155], v152 offset:3072
	ds_read_b128 v[156:159], v168
	ds_read_b128 v[160:163], v168 offset:1024
	ds_read_b128 v[164:167], v168 offset:2048
	ds_read_b128 v[168:171], v168 offset:3072
	v_lshl_add_u64 v[204:205], s[18:19], 0, v[132:133]
	s_add_i32 m0, s40, 0xc000
	ds_read_b128 v[172:175], v147
	ds_read_b128 v[176:179], v147 offset:1024
	ds_read_b128 v[180:183], v147 offset:2048
	ds_read_b128 v[184:187], v147 offset:3072
	ds_read_b128 v[188:191], v147 offset:4096
	ds_read_b128 v[192:195], v147 offset:5120
	ds_read_b128 v[196:199], v147 offset:6144
	ds_read_b128 v[200:203], v147 offset:7168
	global_load_lds_dwordx4 v[204:205], off
	v_lshl_add_u64 v[204:205], s[18:19], 0, v[134:135]
	s_add_i32 m0, s40, 0xe000
	s_nop 0
	global_load_lds_dwordx4 v[204:205], off
	s_waitcnt vmcnt(8)
	s_waitcnt lgkmcnt(0)
	s_barrier
	s_setprio 1
	s_waitcnt lgkmcnt(0)
	v_mfma_f32_16x16x32_bf16 v[126:129], v[136:139], v[172:175], 0
	v_mfma_f32_16x16x32_bf16 v[122:125], v[148:151], v[172:175], 0
	v_mfma_f32_16x16x32_bf16 v[114:117], v[136:139], v[180:183], 0
	v_mfma_f32_16x16x32_bf16 v[110:113], v[148:151], v[180:183], 0
	v_mfma_f32_16x16x32_bf16 v[98:101], v[136:139], v[188:191], 0
	v_mfma_f32_16x16x32_bf16 v[94:97], v[148:151], v[188:191], 0
	v_mfma_f32_16x16x32_bf16 v[82:85], v[136:139], v[196:199], 0
	v_mfma_f32_16x16x32_bf16 v[78:81], v[148:151], v[196:199], 0
	v_mfma_f32_16x16x32_bf16 v[126:129], v[140:143], v[176:179], v[126:129]
	v_mfma_f32_16x16x32_bf16 v[122:125], v[152:155], v[176:179], v[122:125]
	v_mfma_f32_16x16x32_bf16 v[114:117], v[140:143], v[184:187], v[114:117]
	v_mfma_f32_16x16x32_bf16 v[110:113], v[152:155], v[184:187], v[110:113]
	v_mfma_f32_16x16x32_bf16 v[98:101], v[140:143], v[192:195], v[98:101]
	v_mfma_f32_16x16x32_bf16 v[94:97], v[152:155], v[192:195], v[94:97]
	v_mfma_f32_16x16x32_bf16 v[82:85], v[140:143], v[200:203], v[82:85]
	v_mfma_f32_16x16x32_bf16 v[78:81], v[152:155], v[200:203], v[78:81]
	s_setprio 0
	s_setprio 1
	v_mfma_f32_16x16x32_bf16 v[118:121], v[156:159], v[172:175], 0
	v_mfma_f32_16x16x32_bf16 v[106:109], v[164:167], v[172:175], 0
	v_mfma_f32_16x16x32_bf16 v[102:105], v[156:159], v[180:183], 0
	v_mfma_f32_16x16x32_bf16 v[90:93], v[164:167], v[180:183], 0
	v_mfma_f32_16x16x32_bf16 v[86:89], v[156:159], v[188:191], 0
	v_mfma_f32_16x16x32_bf16 v[74:77], v[164:167], v[188:191], 0
	v_mfma_f32_16x16x32_bf16 v[70:73], v[156:159], v[196:199], 0
	v_mfma_f32_16x16x32_bf16 v[66:69], v[164:167], v[196:199], 0
	v_mfma_f32_16x16x32_bf16 v[118:121], v[160:163], v[176:179], v[118:121]
	v_mfma_f32_16x16x32_bf16 v[106:109], v[168:171], v[176:179], v[106:109]
	v_mfma_f32_16x16x32_bf16 v[102:105], v[160:163], v[184:187], v[102:105]
	v_mfma_f32_16x16x32_bf16 v[90:93], v[168:171], v[184:187], v[90:93]
	v_mfma_f32_16x16x32_bf16 v[86:89], v[160:163], v[192:195], v[86:89]
	v_mfma_f32_16x16x32_bf16 v[74:77], v[168:171], v[192:195], v[74:77]
	v_mfma_f32_16x16x32_bf16 v[70:73], v[160:163], v[200:203], v[70:73]
	v_mfma_f32_16x16x32_bf16 v[66:69], v[168:171], v[200:203], v[66:69]
	s_setprio 0
	s_barrier
	s_add_i32 s18, s70, s12
	v_lshl_add_u64 v[204:205], s[22:23], 0, v[0:1]
	s_mov_b32 m0, s18
	ds_read_b128 v[172:175], v147 offset:16384
	ds_read_b128 v[176:179], v147 offset:17408
	ds_read_b128 v[180:183], v147 offset:18432
	ds_read_b128 v[184:187], v147 offset:19456
	ds_read_b128 v[188:191], v147 offset:20480
	ds_read_b128 v[192:195], v147 offset:21504
	ds_read_b128 v[196:199], v147 offset:22528
	ds_read_b128 v[200:203], v147 offset:23552
	global_load_lds_dwordx4 v[204:205], off
	s_add_i32 m0, s18, 0x2000
	s_add_u32 s18, s22, 0xb0000
	v_lshl_add_u64 v[216:217], s[22:23], 0, v[130:131]
	s_addc_u32 s19, s23, 0
	s_add_i32 s70, s76, s12
	global_load_lds_dwordx4 v[216:217], off
	v_lshl_add_u64 v[218:219], s[18:19], 0, v[0:1]
	s_mov_b32 m0, s70
	v_lshl_add_u64 v[220:221], s[24:25], 0, v[130:131]
	global_load_lds_dwordx4 v[218:219], off
	v_lshl_add_u64 v[218:219], s[18:19], 0, v[130:131]
	s_add_i32 m0, s70, 0x2000
	s_nop 0
	global_load_lds_dwordx4 v[218:219], off
	v_lshl_add_u64 v[218:219], s[24:25], 0, v[0:1]
	s_mov_b32 m0, s40
	s_nop 0
	global_load_lds_dwordx4 v[218:219], off
	s_mov_b32 m0, s41
	s_nop 0
	global_load_lds_dwordx4 v[220:221], off
	s_waitcnt vmcnt(8)
	s_waitcnt lgkmcnt(0)
	s_barrier
	s_setprio 1
	s_waitcnt lgkmcnt(0)
	v_mfma_f32_16x16x32_bf16 v[62:65], v[136:139], v[172:175], 0
	v_mfma_f32_16x16x32_bf16 v[58:61], v[148:151], v[172:175], 0
	v_mfma_f32_16x16x32_bf16 v[50:53], v[136:139], v[180:183], 0
	v_mfma_f32_16x16x32_bf16 v[46:49], v[148:151], v[180:183], 0
	v_mfma_f32_16x16x32_bf16 v[34:37], v[136:139], v[188:191], 0
	v_mfma_f32_16x16x32_bf16 v[30:33], v[148:151], v[188:191], 0
	v_mfma_f32_16x16x32_bf16 v[18:21], v[136:139], v[196:199], 0
	v_mfma_f32_16x16x32_bf16 v[14:17], v[148:151], v[196:199], 0
	v_mfma_f32_16x16x32_bf16 v[62:65], v[140:143], v[176:179], v[62:65]
	v_mfma_f32_16x16x32_bf16 v[58:61], v[152:155], v[176:179], v[58:61]
	v_mfma_f32_16x16x32_bf16 v[50:53], v[140:143], v[184:187], v[50:53]
	v_mfma_f32_16x16x32_bf16 v[46:49], v[152:155], v[184:187], v[46:49]
	v_mfma_f32_16x16x32_bf16 v[34:37], v[140:143], v[192:195], v[34:37]
	v_mfma_f32_16x16x32_bf16 v[30:33], v[152:155], v[192:195], v[30:33]
	v_mfma_f32_16x16x32_bf16 v[18:21], v[140:143], v[200:203], v[18:21]
	v_mfma_f32_16x16x32_bf16 v[14:17], v[152:155], v[200:203], v[14:17]
	s_setprio 0
	s_setprio 1
	v_mfma_f32_16x16x32_bf16 v[54:57], v[156:159], v[172:175], 0
	v_mfma_f32_16x16x32_bf16 v[42:45], v[164:167], v[172:175], 0
	v_mfma_f32_16x16x32_bf16 v[38:41], v[156:159], v[180:183], 0
	v_mfma_f32_16x16x32_bf16 v[26:29], v[164:167], v[180:183], 0
	v_mfma_f32_16x16x32_bf16 v[22:25], v[156:159], v[188:191], 0
	v_mfma_f32_16x16x32_bf16 v[10:13], v[164:167], v[188:191], 0
	v_mfma_f32_16x16x32_bf16 v[6:9], v[156:159], v[196:199], 0
	v_mfma_f32_16x16x32_bf16 v[2:5], v[164:167], v[196:199], 0
	v_mfma_f32_16x16x32_bf16 v[54:57], v[160:163], v[176:179], v[54:57]
	v_mfma_f32_16x16x32_bf16 v[42:45], v[168:171], v[176:179], v[42:45]
	v_mfma_f32_16x16x32_bf16 v[38:41], v[160:163], v[184:187], v[38:41]
	v_mfma_f32_16x16x32_bf16 v[26:29], v[168:171], v[184:187], v[26:29]
	v_mfma_f32_16x16x32_bf16 v[22:25], v[160:163], v[192:195], v[22:25]
	v_mfma_f32_16x16x32_bf16 v[10:13], v[168:171], v[192:195], v[10:13]
	v_mfma_f32_16x16x32_bf16 v[6:9], v[160:163], v[200:203], v[6:9]
	v_mfma_f32_16x16x32_bf16 v[2:5], v[168:171], v[200:203], v[2:5]
	s_setprio 0
	s_barrier
	s_add_i32 s70, 0, 0x18000
	s_add_i32 s76, 0, 0x1c000
	v_add_u32_e32 v152, s70, v145
	v_add_u32_e32 v168, s76, v145
	ds_read_b128 v[136:139], v152
	ds_read_b128 v[140:143], v152 offset:1024
	ds_read_b128 v[148:151], v152 offset:2048
	ds_read_b128 v[152:155], v152 offset:3072
	ds_read_b128 v[156:159], v168
	ds_read_b128 v[160:163], v168 offset:1024
	ds_read_b128 v[164:167], v168 offset:2048
	ds_read_b128 v[168:171], v168 offset:3072
	s_add_u32 s18, s24, 0xb0000
	s_addc_u32 s19, s25, 0
	s_mov_b32 m0, s42
	v_lshl_add_u64 v[222:223], s[18:19], 0, v[0:1]
	ds_read_b128 v[172:175], v147 offset:32768
	ds_read_b128 v[176:179], v147 offset:33792
	ds_read_b128 v[180:183], v147 offset:34816
	ds_read_b128 v[184:187], v147 offset:35840
	ds_read_b128 v[188:191], v147 offset:36864
	ds_read_b128 v[192:195], v147 offset:37888
	ds_read_b128 v[196:199], v147 offset:38912
	ds_read_b128 v[200:203], v147 offset:39936
	global_load_lds_dwordx4 v[222:223], off
	v_lshl_add_u64 v[222:223], s[18:19], 0, v[130:131]
	s_mov_b32 m0, s43
	s_nop 0
	global_load_lds_dwordx4 v[222:223], off
	s_waitcnt vmcnt(8)
	s_waitcnt lgkmcnt(0)
	s_barrier
	s_setprio 1
	s_waitcnt lgkmcnt(0)
	v_mfma_f32_16x16x32_bf16 v[126:129], v[136:139], v[172:175], v[126:129]
	v_mfma_f32_16x16x32_bf16 v[122:125], v[148:151], v[172:175], v[122:125]
	v_mfma_f32_16x16x32_bf16 v[114:117], v[136:139], v[180:183], v[114:117]
	v_mfma_f32_16x16x32_bf16 v[110:113], v[148:151], v[180:183], v[110:113]
	v_mfma_f32_16x16x32_bf16 v[98:101], v[136:139], v[188:191], v[98:101]
	v_mfma_f32_16x16x32_bf16 v[94:97], v[148:151], v[188:191], v[94:97]
	v_mfma_f32_16x16x32_bf16 v[82:85], v[136:139], v[196:199], v[82:85]
	v_mfma_f32_16x16x32_bf16 v[78:81], v[148:151], v[196:199], v[78:81]
	v_mfma_f32_16x16x32_bf16 v[126:129], v[140:143], v[176:179], v[126:129]
	v_mfma_f32_16x16x32_bf16 v[122:125], v[152:155], v[176:179], v[122:125]
	v_mfma_f32_16x16x32_bf16 v[114:117], v[140:143], v[184:187], v[114:117]
	v_mfma_f32_16x16x32_bf16 v[110:113], v[152:155], v[184:187], v[110:113]
	v_mfma_f32_16x16x32_bf16 v[98:101], v[140:143], v[192:195], v[98:101]
	v_mfma_f32_16x16x32_bf16 v[94:97], v[152:155], v[192:195], v[94:97]
	v_mfma_f32_16x16x32_bf16 v[82:85], v[140:143], v[200:203], v[82:85]
	v_mfma_f32_16x16x32_bf16 v[78:81], v[152:155], v[200:203], v[78:81]
	s_setprio 0
	s_setprio 1
	v_mfma_f32_16x16x32_bf16 v[118:121], v[156:159], v[172:175], v[118:121]
	v_mfma_f32_16x16x32_bf16 v[106:109], v[164:167], v[172:175], v[106:109]
	v_mfma_f32_16x16x32_bf16 v[102:105], v[156:159], v[180:183], v[102:105]
	v_mfma_f32_16x16x32_bf16 v[90:93], v[164:167], v[180:183], v[90:93]
	v_mfma_f32_16x16x32_bf16 v[86:89], v[156:159], v[188:191], v[86:89]
	v_mfma_f32_16x16x32_bf16 v[74:77], v[164:167], v[188:191], v[74:77]
	v_mfma_f32_16x16x32_bf16 v[70:73], v[156:159], v[196:199], v[70:73]
	v_mfma_f32_16x16x32_bf16 v[66:69], v[164:167], v[196:199], v[66:69]
	v_mfma_f32_16x16x32_bf16 v[118:121], v[160:163], v[176:179], v[118:121]
	v_mfma_f32_16x16x32_bf16 v[106:109], v[168:171], v[176:179], v[106:109]
	v_mfma_f32_16x16x32_bf16 v[102:105], v[160:163], v[184:187], v[102:105]
	v_mfma_f32_16x16x32_bf16 v[90:93], v[168:171], v[184:187], v[90:93]
	v_mfma_f32_16x16x32_bf16 v[86:89], v[160:163], v[192:195], v[86:89]
	v_mfma_f32_16x16x32_bf16 v[74:77], v[168:171], v[192:195], v[74:77]
	v_mfma_f32_16x16x32_bf16 v[70:73], v[160:163], v[200:203], v[70:73]
	v_mfma_f32_16x16x32_bf16 v[66:69], v[168:171], v[200:203], v[66:69]
	s_setprio 0
	s_barrier
	s_add_i32 s18, s70, s12
	v_lshl_add_u64 v[204:205], v[204:205], 0, s[30:31]
	s_mov_b32 m0, s18
	ds_read_b128 v[172:175], v147 offset:49152
	ds_read_b128 v[176:179], v147 offset:50176
	ds_read_b128 v[180:183], v147 offset:51200
	ds_read_b128 v[184:187], v147 offset:52224
	ds_read_b128 v[188:191], v147 offset:53248
	ds_read_b128 v[192:195], v147 offset:54272
	ds_read_b128 v[196:199], v147 offset:55296
	ds_read_b128 v[200:203], v147 offset:56320
	global_load_lds_dwordx4 v[204:205], off
	s_add_i32 m0, s18, 0x2000
	s_add_u32 s18, s22, 0xb0080
	v_lshl_add_u64 v[204:205], v[216:217], 0, s[30:31]
	s_addc_u32 s19, s23, 0
	s_add_i32 s22, s76, s12
	global_load_lds_dwordx4 v[204:205], off
	v_lshl_add_u64 v[204:205], s[18:19], 0, v[0:1]
	s_mov_b32 m0, s22
	s_nop 0
	global_load_lds_dwordx4 v[204:205], off
	v_lshl_add_u64 v[204:205], s[18:19], 0, v[130:131]
	s_add_i32 m0, s22, 0x2000
	s_nop 0
	global_load_lds_dwordx4 v[204:205], off
	v_lshl_add_u64 v[204:205], v[218:219], 0, s[30:31]
	s_mov_b32 m0, s50
	s_nop 0
	global_load_lds_dwordx4 v[204:205], off
	v_lshl_add_u64 v[204:205], v[220:221], 0, s[30:31]
	s_mov_b32 m0, s51
	s_nop 0
	global_load_lds_dwordx4 v[204:205], off
	s_waitcnt vmcnt(8)
	s_waitcnt lgkmcnt(0)
	s_barrier
	s_setprio 1
	s_waitcnt lgkmcnt(0)
	v_mfma_f32_16x16x32_bf16 v[62:65], v[136:139], v[172:175], v[62:65]
	v_mfma_f32_16x16x32_bf16 v[58:61], v[148:151], v[172:175], v[58:61]
	v_mfma_f32_16x16x32_bf16 v[50:53], v[136:139], v[180:183], v[50:53]
	v_mfma_f32_16x16x32_bf16 v[46:49], v[148:151], v[180:183], v[46:49]
	v_mfma_f32_16x16x32_bf16 v[34:37], v[136:139], v[188:191], v[34:37]
	v_mfma_f32_16x16x32_bf16 v[30:33], v[148:151], v[188:191], v[30:33]
	v_mfma_f32_16x16x32_bf16 v[18:21], v[136:139], v[196:199], v[18:21]
	v_mfma_f32_16x16x32_bf16 v[14:17], v[148:151], v[196:199], v[14:17]
	v_mfma_f32_16x16x32_bf16 v[62:65], v[140:143], v[176:179], v[62:65]
	v_mfma_f32_16x16x32_bf16 v[58:61], v[152:155], v[176:179], v[58:61]
	v_mfma_f32_16x16x32_bf16 v[50:53], v[140:143], v[184:187], v[50:53]
	v_mfma_f32_16x16x32_bf16 v[46:49], v[152:155], v[184:187], v[46:49]
	v_mfma_f32_16x16x32_bf16 v[34:37], v[140:143], v[192:195], v[34:37]
	v_mfma_f32_16x16x32_bf16 v[30:33], v[152:155], v[192:195], v[30:33]
	v_mfma_f32_16x16x32_bf16 v[18:21], v[140:143], v[200:203], v[18:21]
	v_mfma_f32_16x16x32_bf16 v[14:17], v[152:155], v[200:203], v[14:17]
	s_setprio 0
	s_setprio 1
	v_mfma_f32_16x16x32_bf16 v[54:57], v[156:159], v[172:175], v[54:57]
	v_mfma_f32_16x16x32_bf16 v[42:45], v[164:167], v[172:175], v[42:45]
	v_mfma_f32_16x16x32_bf16 v[38:41], v[156:159], v[180:183], v[38:41]
	v_mfma_f32_16x16x32_bf16 v[26:29], v[164:167], v[180:183], v[26:29]
	v_mfma_f32_16x16x32_bf16 v[22:25], v[156:159], v[188:191], v[22:25]
	v_mfma_f32_16x16x32_bf16 v[10:13], v[164:167], v[188:191], v[10:13]
	v_mfma_f32_16x16x32_bf16 v[6:9], v[156:159], v[196:199], v[6:9]
	v_mfma_f32_16x16x32_bf16 v[2:5], v[164:167], v[196:199], v[2:5]
	v_mfma_f32_16x16x32_bf16 v[54:57], v[160:163], v[176:179], v[54:57]
	v_mfma_f32_16x16x32_bf16 v[42:45], v[168:171], v[176:179], v[42:45]
	v_mfma_f32_16x16x32_bf16 v[38:41], v[160:163], v[184:187], v[38:41]
	v_mfma_f32_16x16x32_bf16 v[26:29], v[168:171], v[184:187], v[26:29]
	v_mfma_f32_16x16x32_bf16 v[22:25], v[160:163], v[192:195], v[22:25]
	v_mfma_f32_16x16x32_bf16 v[10:13], v[168:171], v[192:195], v[10:13]
	v_mfma_f32_16x16x32_bf16 v[6:9], v[160:163], v[200:203], v[6:9]
	v_mfma_f32_16x16x32_bf16 v[2:5], v[168:171], v[200:203], v[2:5]
	s_setprio 0
	s_barrier
	s_add_i32 s65, s65, 2
	s_add_u32 s48, s48, 0x100
	s_addc_u32 s49, s49, 0
	s_cmp_gt_u32 s65, 41
	s_mov_b64 s[18:19], s[20:21]
	s_cbranch_scc0 .LBB0_284
	s_branch .Lgemm_kexit_1

.LBB0_417:
	s_ashr_i32 s1, s0, 31
	s_lshl_b64 s[14:15], s[0:1], 19
	s_add_u32 s14, s34, s14
	s_addc_u32 s15, s35, s15
	s_and_b64 s[18:19], s[46:47], exec
	s_cselect_b32 s1, s15, s21
	s_cselect_b32 s57, s14, s20
	s_ashr_i32 s11, s10, 31
	s_lshl_b64 s[18:19], s[10:11], 19
	s_add_u32 s18, s36, s18
	s_addc_u32 s19, s37, s19
	s_and_b64 s[24:25], s[46:47], exec
	s_cselect_b32 s11, s19, s23
	s_cselect_b32 s58, s18, s22
	s_add_u32 s20, s20, 0x40080
	s_addc_u32 s21, s21, 0
	s_add_u32 s59, s22, 0x100
	s_addc_u32 s60, s23, 0
	s_mov_b32 s61, -2
	s_add_u32 s22, s20, 0xfffc0080
	s_addc_u32 s23, s21, -1
	s_add_i32 s64, 0, 0x10000
	s_cmp_eq_u32 s61, 12
	s_cselect_b32 s25, s1, s23
	s_cselect_b32 s24, s57, s22
	v_add_u32_e32 v140, s64, v144
	s_cselect_b32 s23, s11, s60
	s_cselect_b32 s22, s58, s59
	s_add_i32 s70, 0, 0x14000
	ds_read_b128 v[148:151], v140
	ds_read_b128 v[152:155], v140 offset:1024
	ds_read_b128 v[156:159], v140 offset:2048
	ds_read_b128 v[160:163], v140 offset:3072
	v_add_u32_e32 v140, s70, v144
	ds_read_b128 v[164:167], v140
	ds_read_b128 v[168:171], v140 offset:1024
	ds_read_b128 v[172:175], v140 offset:2048
	ds_read_b128 v[176:179], v140 offset:3072
	v_lshl_add_u64 v[142:143], s[20:21], 0, v[136:137]
	s_add_i32 m0, s40, 0xc000
	ds_read_b128 v[180:183], v146
	ds_read_b128 v[184:187], v146 offset:1024
	ds_read_b128 v[188:191], v146 offset:2048
	ds_read_b128 v[192:195], v146 offset:3072
	ds_read_b128 v[196:199], v146 offset:4096
	ds_read_b128 v[200:203], v146 offset:5120
	ds_read_b128 v[216:219], v146 offset:6144
	ds_read_b128 v[220:223], v146 offset:7168
	global_load_lds_dwordx4 v[142:143], off
	v_lshl_add_u64 v[142:143], s[20:21], 0, v[138:139]
	s_add_i32 m0, s40, 0xe000
	s_nop 0
	global_load_lds_dwordx4 v[142:143], off
	s_waitcnt vmcnt(8)
	s_waitcnt lgkmcnt(0)
	s_barrier
	s_setprio 1
	s_waitcnt lgkmcnt(0)
	v_mfma_f32_16x16x32_bf16 v[126:129], v[148:151], v[180:183], 0
	v_mfma_f32_16x16x32_bf16 v[122:125], v[156:159], v[180:183], 0
	v_mfma_f32_16x16x32_bf16 v[114:117], v[148:151], v[188:191], 0
	v_mfma_f32_16x16x32_bf16 v[106:109], v[156:159], v[188:191], 0
	v_mfma_f32_16x16x32_bf16 v[98:101], v[148:151], v[196:199], 0
	v_mfma_f32_16x16x32_bf16 v[90:93], v[156:159], v[196:199], 0
	v_mfma_f32_16x16x32_bf16 v[82:85], v[148:151], v[216:219], 0
	v_mfma_f32_16x16x32_bf16 v[74:77], v[156:159], v[216:219], 0
	v_mfma_f32_16x16x32_bf16 v[126:129], v[152:155], v[184:187], v[126:129]
	v_mfma_f32_16x16x32_bf16 v[122:125], v[160:163], v[184:187], v[122:125]
	v_mfma_f32_16x16x32_bf16 v[114:117], v[152:155], v[192:195], v[114:117]
	v_mfma_f32_16x16x32_bf16 v[106:109], v[160:163], v[192:195], v[106:109]
	v_mfma_f32_16x16x32_bf16 v[98:101], v[152:155], v[200:203], v[98:101]
	v_mfma_f32_16x16x32_bf16 v[90:93], v[160:163], v[200:203], v[90:93]
	v_mfma_f32_16x16x32_bf16 v[82:85], v[152:155], v[220:223], v[82:85]
	v_mfma_f32_16x16x32_bf16 v[74:77], v[160:163], v[220:223], v[74:77]
	s_setprio 0
	s_setprio 1
	v_mfma_f32_16x16x32_bf16 v[118:121], v[164:167], v[180:183], 0
	v_mfma_f32_16x16x32_bf16 v[110:113], v[172:175], v[180:183], 0
	v_mfma_f32_16x16x32_bf16 v[102:105], v[164:167], v[188:191], 0
	v_mfma_f32_16x16x32_bf16 v[94:97], v[172:175], v[188:191], 0
	v_mfma_f32_16x16x32_bf16 v[86:89], v[164:167], v[196:199], 0
	v_mfma_f32_16x16x32_bf16 v[78:81], v[172:175], v[196:199], 0
	v_mfma_f32_16x16x32_bf16 v[70:73], v[164:167], v[216:219], 0
	v_mfma_f32_16x16x32_bf16 v[66:69], v[172:175], v[216:219], 0
	v_mfma_f32_16x16x32_bf16 v[118:121], v[168:171], v[184:187], v[118:121]
	v_mfma_f32_16x16x32_bf16 v[110:113], v[176:179], v[184:187], v[110:113]
	v_mfma_f32_16x16x32_bf16 v[102:105], v[168:171], v[192:195], v[102:105]
	v_mfma_f32_16x16x32_bf16 v[94:97], v[176:179], v[192:195], v[94:97]
	v_mfma_f32_16x16x32_bf16 v[86:89], v[168:171], v[200:203], v[86:89]
	v_mfma_f32_16x16x32_bf16 v[78:81], v[176:179], v[200:203], v[78:81]
	v_mfma_f32_16x16x32_bf16 v[70:73], v[168:171], v[220:223], v[70:73]
	v_mfma_f32_16x16x32_bf16 v[66:69], v[176:179], v[220:223], v[66:69]
	s_setprio 0
	s_barrier
	s_add_i32 s64, s64, s12
	v_lshl_add_u64 v[142:143], s[22:23], 0, v[0:1]
	s_mov_b32 m0, s64
	ds_read_b128 v[180:183], v146 offset:16384
	ds_read_b128 v[184:187], v146 offset:17408
	ds_read_b128 v[188:191], v146 offset:18432
	ds_read_b128 v[192:195], v146 offset:19456
	ds_read_b128 v[196:199], v146 offset:20480
	ds_read_b128 v[200:203], v146 offset:21504
	ds_read_b128 v[216:219], v146 offset:22528
	ds_read_b128 v[220:223], v146 offset:23552
	global_load_lds_dwordx4 v[142:143], off
	s_add_i32 m0, s64, 0x2000
	s_add_u32 s64, s22, 0x40000
	v_lshl_add_u64 v[204:205], s[22:23], 0, v[130:131]
	s_addc_u32 s65, s23, 0
	s_add_i32 s70, s70, s12
	global_load_lds_dwordx4 v[204:205], off
	v_lshl_add_u64 v[224:225], s[64:65], 0, v[0:1]
	s_mov_b32 m0, s70
	v_lshl_add_u64 v[228:229], s[24:25], 0, v[132:133]
	global_load_lds_dwordx4 v[224:225], off
	v_lshl_add_u64 v[224:225], s[64:65], 0, v[130:131]
	s_add_i32 m0, s70, 0x2000
	s_nop 0
	global_load_lds_dwordx4 v[224:225], off
	v_lshl_add_u64 v[224:225], s[24:25], 0, v[134:135]
	s_mov_b32 m0, s40
	s_nop 0
	global_load_lds_dwordx4 v[224:225], off
	s_mov_b32 m0, s41
	s_nop 0
	global_load_lds_dwordx4 v[228:229], off
	s_waitcnt vmcnt(8)
	s_waitcnt lgkmcnt(0)
	s_barrier
	s_setprio 1
	s_waitcnt lgkmcnt(0)
	v_mfma_f32_16x16x32_bf16 v[62:65], v[148:151], v[180:183], 0
	v_mfma_f32_16x16x32_bf16 v[58:61], v[156:159], v[180:183], 0
	v_mfma_f32_16x16x32_bf16 v[50:53], v[148:151], v[188:191], 0
	v_mfma_f32_16x16x32_bf16 v[42:45], v[156:159], v[188:191], 0
	v_mfma_f32_16x16x32_bf16 v[34:37], v[148:151], v[196:199], 0
	v_mfma_f32_16x16x32_bf16 v[26:29], v[156:159], v[196:199], 0
	v_mfma_f32_16x16x32_bf16 v[18:21], v[148:151], v[216:219], 0
	v_mfma_f32_16x16x32_bf16 v[10:13], v[156:159], v[216:219], 0
	v_mfma_f32_16x16x32_bf16 v[62:65], v[152:155], v[184:187], v[62:65]
	v_mfma_f32_16x16x32_bf16 v[58:61], v[160:163], v[184:187], v[58:61]
	v_mfma_f32_16x16x32_bf16 v[50:53], v[152:155], v[192:195], v[50:53]
	v_mfma_f32_16x16x32_bf16 v[42:45], v[160:163], v[192:195], v[42:45]
	v_mfma_f32_16x16x32_bf16 v[34:37], v[152:155], v[200:203], v[34:37]
	v_mfma_f32_16x16x32_bf16 v[26:29], v[160:163], v[200:203], v[26:29]
	v_mfma_f32_16x16x32_bf16 v[18:21], v[152:155], v[220:223], v[18:21]
	v_mfma_f32_16x16x32_bf16 v[10:13], v[160:163], v[220:223], v[10:13]
	s_setprio 0
	s_setprio 1
	v_mfma_f32_16x16x32_bf16 v[54:57], v[164:167], v[180:183], 0
	v_mfma_f32_16x16x32_bf16 v[46:49], v[172:175], v[180:183], 0
	v_mfma_f32_16x16x32_bf16 v[38:41], v[164:167], v[188:191], 0
	v_mfma_f32_16x16x32_bf16 v[30:33], v[172:175], v[188:191], 0
	v_mfma_f32_16x16x32_bf16 v[22:25], v[164:167], v[196:199], 0
	v_mfma_f32_16x16x32_bf16 v[14:17], v[172:175], v[196:199], 0
	v_mfma_f32_16x16x32_bf16 v[6:9], v[164:167], v[216:219], 0
	v_mfma_f32_16x16x32_bf16 v[2:5], v[172:175], v[216:219], 0
	v_mfma_f32_16x16x32_bf16 v[54:57], v[168:171], v[184:187], v[54:57]
	v_mfma_f32_16x16x32_bf16 v[46:49], v[176:179], v[184:187], v[46:49]
	v_mfma_f32_16x16x32_bf16 v[38:41], v[168:171], v[192:195], v[38:41]
	v_mfma_f32_16x16x32_bf16 v[30:33], v[176:179], v[192:195], v[30:33]
	v_mfma_f32_16x16x32_bf16 v[22:25], v[168:171], v[200:203], v[22:25]
	v_mfma_f32_16x16x32_bf16 v[14:17], v[176:179], v[200:203], v[14:17]
	v_mfma_f32_16x16x32_bf16 v[6:9], v[168:171], v[220:223], v[6:9]
	v_mfma_f32_16x16x32_bf16 v[2:5], v[176:179], v[220:223], v[2:5]
	s_setprio 0
	s_barrier
	s_add_i32 s64, 0, 0x18000
	v_add_u32_e32 v140, s64, v144
	s_add_i32 s65, 0, 0x1c000
	ds_read_b128 v[148:151], v140
	ds_read_b128 v[152:155], v140 offset:1024
	ds_read_b128 v[156:159], v140 offset:2048
	ds_read_b128 v[160:163], v140 offset:3072
	v_add_u32_e32 v140, s65, v144
	ds_read_b128 v[164:167], v140
	ds_read_b128 v[168:171], v140 offset:1024
	ds_read_b128 v[172:175], v140 offset:2048
	ds_read_b128 v[176:179], v140 offset:3072
	s_add_u32 s24, s24, 0x40000
	s_addc_u32 s25, s25, 0
	s_mov_b32 m0, s42
	v_lshl_add_u64 v[230:231], s[24:25], 0, v[134:135]
	ds_read_b128 v[180:183], v146 offset:32768
	ds_read_b128 v[184:187], v146 offset:33792
	ds_read_b128 v[188:191], v146 offset:34816
	ds_read_b128 v[192:195], v146 offset:35840
	ds_read_b128 v[196:199], v146 offset:36864
	ds_read_b128 v[200:203], v146 offset:37888
	ds_read_b128 v[216:219], v146 offset:38912
	ds_read_b128 v[220:223], v146 offset:39936
	global_load_lds_dwordx4 v[230:231], off
	v_lshl_add_u64 v[230:231], s[24:25], 0, v[132:133]
	s_mov_b32 m0, s43
	s_nop 0
	global_load_lds_dwordx4 v[230:231], off
	s_waitcnt vmcnt(8)
	s_waitcnt lgkmcnt(0)
	s_barrier
	s_setprio 1
	s_waitcnt lgkmcnt(0)
	v_mfma_f32_16x16x32_bf16 v[126:129], v[148:151], v[180:183], v[126:129]
	v_mfma_f32_16x16x32_bf16 v[122:125], v[156:159], v[180:183], v[122:125]
	v_mfma_f32_16x16x32_bf16 v[114:117], v[148:151], v[188:191], v[114:117]
	v_mfma_f32_16x16x32_bf16 v[106:109], v[156:159], v[188:191], v[106:109]
	v_mfma_f32_16x16x32_bf16 v[98:101], v[148:151], v[196:199], v[98:101]
	v_mfma_f32_16x16x32_bf16 v[90:93], v[156:159], v[196:199], v[90:93]
	v_mfma_f32_16x16x32_bf16 v[82:85], v[148:151], v[216:219], v[82:85]
	v_mfma_f32_16x16x32_bf16 v[74:77], v[156:159], v[216:219], v[74:77]
	v_mfma_f32_16x16x32_bf16 v[126:129], v[152:155], v[184:187], v[126:129]
	v_mfma_f32_16x16x32_bf16 v[122:125], v[160:163], v[184:187], v[122:125]
	v_mfma_f32_16x16x32_bf16 v[114:117], v[152:155], v[192:195], v[114:117]
	v_mfma_f32_16x16x32_bf16 v[106:109], v[160:163], v[192:195], v[106:109]
	v_mfma_f32_16x16x32_bf16 v[98:101], v[152:155], v[200:203], v[98:101]
	v_mfma_f32_16x16x32_bf16 v[90:93], v[160:163], v[200:203], v[90:93]
	v_mfma_f32_16x16x32_bf16 v[82:85], v[152:155], v[220:223], v[82:85]
	v_mfma_f32_16x16x32_bf16 v[74:77], v[160:163], v[220:223], v[74:77]
	s_setprio 0
	s_setprio 1
	v_mfma_f32_16x16x32_bf16 v[118:121], v[164:167], v[180:183], v[118:121]
	v_mfma_f32_16x16x32_bf16 v[110:113], v[172:175], v[180:183], v[110:113]
	v_mfma_f32_16x16x32_bf16 v[102:105], v[164:167], v[188:191], v[102:105]
	v_mfma_f32_16x16x32_bf16 v[94:97], v[172:175], v[188:191], v[94:97]
	v_mfma_f32_16x16x32_bf16 v[86:89], v[164:167], v[196:199], v[86:89]
	v_mfma_f32_16x16x32_bf16 v[78:81], v[172:175], v[196:199], v[78:81]
	v_mfma_f32_16x16x32_bf16 v[70:73], v[164:167], v[216:219], v[70:73]
	v_mfma_f32_16x16x32_bf16 v[66:69], v[172:175], v[216:219], v[66:69]
	v_mfma_f32_16x16x32_bf16 v[118:121], v[168:171], v[184:187], v[118:121]
	v_mfma_f32_16x16x32_bf16 v[110:113], v[176:179], v[184:187], v[110:113]
	v_mfma_f32_16x16x32_bf16 v[102:105], v[168:171], v[192:195], v[102:105]
	v_mfma_f32_16x16x32_bf16 v[94:97], v[176:179], v[192:195], v[94:97]
	v_mfma_f32_16x16x32_bf16 v[86:89], v[168:171], v[200:203], v[86:89]
	v_mfma_f32_16x16x32_bf16 v[78:81], v[176:179], v[200:203], v[78:81]
	v_mfma_f32_16x16x32_bf16 v[70:73], v[168:171], v[220:223], v[70:73]
	v_mfma_f32_16x16x32_bf16 v[66:69], v[176:179], v[220:223], v[66:69]
	s_setprio 0
	s_barrier
	s_add_i32 s24, s64, s12
	v_lshl_add_u64 v[142:143], v[142:143], 0, s[30:31]
	s_mov_b32 m0, s24
	ds_read_b128 v[180:183], v146 offset:49152
	ds_read_b128 v[184:187], v146 offset:50176
	ds_read_b128 v[188:191], v146 offset:51200
	ds_read_b128 v[192:195], v146 offset:52224
	ds_read_b128 v[196:199], v146 offset:53248
	ds_read_b128 v[200:203], v146 offset:54272
	ds_read_b128 v[216:219], v146 offset:55296
	ds_read_b128 v[220:223], v146 offset:56320
	global_load_lds_dwordx4 v[142:143], off
	s_add_i32 m0, s24, 0x2000
	s_add_u32 s22, s22, 0x40080
	v_lshl_add_u64 v[142:143], v[204:205], 0, s[30:31]
	s_addc_u32 s23, s23, 0
	s_add_i32 s24, s65, s12
	global_load_lds_dwordx4 v[142:143], off
	v_lshl_add_u64 v[142:143], s[22:23], 0, v[0:1]
	s_mov_b32 m0, s24
	s_nop 0
	global_load_lds_dwordx4 v[142:143], off
	v_lshl_add_u64 v[142:143], s[22:23], 0, v[130:131]
	s_add_i32 m0, s24, 0x2000
	s_nop 0
	global_load_lds_dwordx4 v[142:143], off
	v_lshl_add_u64 v[142:143], v[224:225], 0, s[30:31]
	s_mov_b32 m0, s48
	s_nop 0
	global_load_lds_dwordx4 v[142:143], off
	v_lshl_add_u64 v[142:143], v[228:229], 0, s[30:31]
	s_mov_b32 m0, s49
	s_nop 0
	global_load_lds_dwordx4 v[142:143], off
	s_waitcnt vmcnt(8)
	s_waitcnt lgkmcnt(0)
	s_barrier
	s_setprio 1
	s_waitcnt lgkmcnt(0)
	v_mfma_f32_16x16x32_bf16 v[62:65], v[148:151], v[180:183], v[62:65]
	v_mfma_f32_16x16x32_bf16 v[58:61], v[156:159], v[180:183], v[58:61]
	v_mfma_f32_16x16x32_bf16 v[50:53], v[148:151], v[188:191], v[50:53]
	v_mfma_f32_16x16x32_bf16 v[42:45], v[156:159], v[188:191], v[42:45]
	v_mfma_f32_16x16x32_bf16 v[34:37], v[148:151], v[196:199], v[34:37]
	v_mfma_f32_16x16x32_bf16 v[26:29], v[156:159], v[196:199], v[26:29]
	v_mfma_f32_16x16x32_bf16 v[18:21], v[148:151], v[216:219], v[18:21]
	v_mfma_f32_16x16x32_bf16 v[10:13], v[156:159], v[216:219], v[10:13]
	v_mfma_f32_16x16x32_bf16 v[62:65], v[152:155], v[184:187], v[62:65]
	v_mfma_f32_16x16x32_bf16 v[58:61], v[160:163], v[184:187], v[58:61]
	v_mfma_f32_16x16x32_bf16 v[50:53], v[152:155], v[192:195], v[50:53]
	v_mfma_f32_16x16x32_bf16 v[42:45], v[160:163], v[192:195], v[42:45]
	v_mfma_f32_16x16x32_bf16 v[34:37], v[152:155], v[200:203], v[34:37]
	v_mfma_f32_16x16x32_bf16 v[26:29], v[160:163], v[200:203], v[26:29]
	v_mfma_f32_16x16x32_bf16 v[18:21], v[152:155], v[220:223], v[18:21]
	v_mfma_f32_16x16x32_bf16 v[10:13], v[160:163], v[220:223], v[10:13]
	s_setprio 0
	s_setprio 1
	v_mfma_f32_16x16x32_bf16 v[54:57], v[164:167], v[180:183], v[54:57]
	v_mfma_f32_16x16x32_bf16 v[46:49], v[172:175], v[180:183], v[46:49]
	v_mfma_f32_16x16x32_bf16 v[38:41], v[164:167], v[188:191], v[38:41]
	v_mfma_f32_16x16x32_bf16 v[30:33], v[172:175], v[188:191], v[30:33]
	v_mfma_f32_16x16x32_bf16 v[22:25], v[164:167], v[196:199], v[22:25]
	v_mfma_f32_16x16x32_bf16 v[14:17], v[172:175], v[196:199], v[14:17]
	v_mfma_f32_16x16x32_bf16 v[6:9], v[164:167], v[216:219], v[6:9]
	v_mfma_f32_16x16x32_bf16 v[2:5], v[172:175], v[216:219], v[2:5]
	v_mfma_f32_16x16x32_bf16 v[54:57], v[168:171], v[184:187], v[54:57]
	v_mfma_f32_16x16x32_bf16 v[46:49], v[176:179], v[184:187], v[46:49]
	v_mfma_f32_16x16x32_bf16 v[38:41], v[168:171], v[192:195], v[38:41]
	v_mfma_f32_16x16x32_bf16 v[30:33], v[176:179], v[192:195], v[30:33]
	v_mfma_f32_16x16x32_bf16 v[22:25], v[168:171], v[200:203], v[22:25]
	v_mfma_f32_16x16x32_bf16 v[14:17], v[176:179], v[200:203], v[14:17]
	v_mfma_f32_16x16x32_bf16 v[6:9], v[168:171], v[220:223], v[6:9]
	v_mfma_f32_16x16x32_bf16 v[2:5], v[176:179], v[220:223], v[2:5]
	s_setprio 0
	s_barrier
	s_add_i32 s61, s61, 2
	s_add_u32 s20, s20, 0x100
	s_addc_u32 s21, s21, 0
	s_add_u32 s59, s59, 0x100
	s_addc_u32 s60, s60, 0
	s_cmp_gt_u32 s61, 13
	s_cbranch_scc0 .LBB0_418
	s_branch .Lgemm_kexit_2

.LBB0_943:
	s_ashr_i32 s11, s10, 31
	s_lshl_b64 s[18:19], s[10:11], 19
	s_add_u32 s18, s34, s18
	s_addc_u32 s19, s35, s19
	s_and_b64 s[24:25], s[40:41], exec
	s_cselect_b32 s11, s19, s21
	s_cselect_b32 s59, s18, s20
	s_ashr_i32 s15, s14, 31
	s_lshl_b64 s[24:25], s[14:15], 19
	s_add_u32 s36, s42, s24
	s_addc_u32 s37, s43, s25
	s_and_b64 s[24:25], s[40:41], exec
	s_cselect_b32 s15, s37, s23
	s_cselect_b32 s60, s36, s22
	s_add_u32 s20, s20, 0x40080
	s_addc_u32 s21, s21, 0
	s_add_u32 s61, s22, 0x100
	s_addc_u32 s64, s23, 0
	s_mov_b32 s65, -2
	s_add_u32 s22, s20, 0xfffc0080
	s_addc_u32 s23, s21, -1
	s_add_i32 s70, 0, 0x10000
	s_cmp_eq_u32 s65, 12
	s_cselect_b32 s25, s11, s23
	s_cselect_b32 s24, s59, s22
	v_add_u32_e32 v140, s70, v143
	s_cselect_b32 s23, s15, s64
	s_cselect_b32 s22, s60, s61
	s_add_i32 s87, 0, 0x14000
	ds_read_b128 v[146:149], v140
	ds_read_b128 v[150:153], v140 offset:1024
	ds_read_b128 v[154:157], v140 offset:2048
	ds_read_b128 v[158:161], v140 offset:3072
	v_add_u32_e32 v140, s87, v143
	ds_read_b128 v[162:165], v140
	ds_read_b128 v[166:169], v140 offset:1024
	ds_read_b128 v[170:173], v140 offset:2048
	ds_read_b128 v[174:177], v140 offset:3072
	v_lshl_add_u64 v[140:141], s[20:21], 0, v[136:137]
	s_add_i32 m0, s44, 0xc000
	ds_read_b128 v[178:181], v145
	ds_read_b128 v[182:185], v145 offset:1024
	ds_read_b128 v[186:189], v145 offset:2048
	ds_read_b128 v[190:193], v145 offset:3072
	ds_read_b128 v[194:197], v145 offset:4096
	ds_read_b128 v[198:201], v145 offset:5120
	ds_read_b128 v[202:205], v145 offset:6144
	ds_read_b128 v[216:219], v145 offset:7168
	global_load_lds_dwordx4 v[140:141], off
	v_lshl_add_u64 v[140:141], s[20:21], 0, v[138:139]
	s_add_i32 m0, s44, 0xe000
	s_nop 0
	global_load_lds_dwordx4 v[140:141], off
	s_waitcnt vmcnt(8)
	s_waitcnt lgkmcnt(0)
	s_barrier
	s_setprio 1
	s_waitcnt lgkmcnt(0)
	v_mfma_f32_16x16x32_bf16 v[126:129], v[146:149], v[178:181], 0
	v_mfma_f32_16x16x32_bf16 v[118:121], v[154:157], v[178:181], 0
	v_mfma_f32_16x16x32_bf16 v[110:113], v[146:149], v[186:189], 0
	v_mfma_f32_16x16x32_bf16 v[102:105], v[154:157], v[186:189], 0
	v_mfma_f32_16x16x32_bf16 v[94:97], v[146:149], v[194:197], 0
	v_mfma_f32_16x16x32_bf16 v[86:89], v[154:157], v[194:197], 0
	v_mfma_f32_16x16x32_bf16 v[78:81], v[146:149], v[202:205], 0
	v_mfma_f32_16x16x32_bf16 v[70:73], v[154:157], v[202:205], 0
	v_mfma_f32_16x16x32_bf16 v[126:129], v[150:153], v[182:185], v[126:129]
	v_mfma_f32_16x16x32_bf16 v[118:121], v[158:161], v[182:185], v[118:121]
	v_mfma_f32_16x16x32_bf16 v[110:113], v[150:153], v[190:193], v[110:113]
	v_mfma_f32_16x16x32_bf16 v[102:105], v[158:161], v[190:193], v[102:105]
	v_mfma_f32_16x16x32_bf16 v[94:97], v[150:153], v[198:201], v[94:97]
	v_mfma_f32_16x16x32_bf16 v[86:89], v[158:161], v[198:201], v[86:89]
	v_mfma_f32_16x16x32_bf16 v[78:81], v[150:153], v[216:219], v[78:81]
	v_mfma_f32_16x16x32_bf16 v[70:73], v[158:161], v[216:219], v[70:73]
	s_setprio 0
	s_setprio 1
	v_mfma_f32_16x16x32_bf16 v[122:125], v[162:165], v[178:181], 0
	v_mfma_f32_16x16x32_bf16 v[114:117], v[170:173], v[178:181], 0
	v_mfma_f32_16x16x32_bf16 v[106:109], v[162:165], v[186:189], 0
	v_mfma_f32_16x16x32_bf16 v[98:101], v[170:173], v[186:189], 0
	v_mfma_f32_16x16x32_bf16 v[90:93], v[162:165], v[194:197], 0
	v_mfma_f32_16x16x32_bf16 v[82:85], v[170:173], v[194:197], 0
	v_mfma_f32_16x16x32_bf16 v[74:77], v[162:165], v[202:205], 0
	v_mfma_f32_16x16x32_bf16 v[66:69], v[170:173], v[202:205], 0
	v_mfma_f32_16x16x32_bf16 v[122:125], v[166:169], v[182:185], v[122:125]
	v_mfma_f32_16x16x32_bf16 v[114:117], v[174:177], v[182:185], v[114:117]
	v_mfma_f32_16x16x32_bf16 v[106:109], v[166:169], v[190:193], v[106:109]
	v_mfma_f32_16x16x32_bf16 v[98:101], v[174:177], v[190:193], v[98:101]
	v_mfma_f32_16x16x32_bf16 v[90:93], v[166:169], v[198:201], v[90:93]
	v_mfma_f32_16x16x32_bf16 v[82:85], v[174:177], v[198:201], v[82:85]
	v_mfma_f32_16x16x32_bf16 v[74:77], v[166:169], v[216:219], v[74:77]
	v_mfma_f32_16x16x32_bf16 v[66:69], v[174:177], v[216:219], v[66:69]
	s_setprio 0
	s_barrier
	s_add_i32 s70, s70, s12
	v_lshl_add_u64 v[140:141], s[22:23], 0, v[0:1]
	s_mov_b32 m0, s70
	ds_read_b128 v[178:181], v145 offset:16384
	ds_read_b128 v[182:185], v145 offset:17408
	ds_read_b128 v[186:189], v145 offset:18432
	ds_read_b128 v[190:193], v145 offset:19456
	ds_read_b128 v[194:197], v145 offset:20480
	ds_read_b128 v[198:201], v145 offset:21504
	ds_read_b128 v[202:205], v145 offset:22528
	ds_read_b128 v[216:219], v145 offset:23552
	global_load_lds_dwordx4 v[140:141], off
	s_add_i32 m0, s70, 0x2000
	s_add_u32 s76, s22, 0x40000
	v_lshl_add_u64 v[220:221], s[22:23], 0, v[130:131]
	s_addc_u32 s77, s23, 0
	s_add_i32 s70, s87, s12
	global_load_lds_dwordx4 v[220:221], off
	v_lshl_add_u64 v[222:223], s[76:77], 0, v[0:1]
	s_mov_b32 m0, s70
	v_lshl_add_u64 v[224:225], s[24:25], 0, v[132:133]
	global_load_lds_dwordx4 v[222:223], off
	v_lshl_add_u64 v[222:223], s[76:77], 0, v[130:131]
	s_add_i32 m0, s70, 0x2000
	s_nop 0
	global_load_lds_dwordx4 v[222:223], off
	v_lshl_add_u64 v[222:223], s[24:25], 0, v[134:135]
	s_mov_b32 m0, s44
	s_nop 0
	global_load_lds_dwordx4 v[222:223], off
	s_mov_b32 m0, s45
	s_nop 0
	global_load_lds_dwordx4 v[224:225], off
	s_waitcnt vmcnt(8)
	s_waitcnt lgkmcnt(0)
	s_barrier
	s_setprio 1
	s_waitcnt lgkmcnt(0)
	v_mfma_f32_16x16x32_bf16 v[62:65], v[146:149], v[178:181], 0
	v_mfma_f32_16x16x32_bf16 v[54:57], v[154:157], v[178:181], 0
	v_mfma_f32_16x16x32_bf16 v[46:49], v[146:149], v[186:189], 0
	v_mfma_f32_16x16x32_bf16 v[38:41], v[154:157], v[186:189], 0
	v_mfma_f32_16x16x32_bf16 v[30:33], v[146:149], v[194:197], 0
	v_mfma_f32_16x16x32_bf16 v[22:25], v[154:157], v[194:197], 0
	v_mfma_f32_16x16x32_bf16 v[14:17], v[146:149], v[202:205], 0
	v_mfma_f32_16x16x32_bf16 v[6:9], v[154:157], v[202:205], 0
	v_mfma_f32_16x16x32_bf16 v[62:65], v[150:153], v[182:185], v[62:65]
	v_mfma_f32_16x16x32_bf16 v[54:57], v[158:161], v[182:185], v[54:57]
	v_mfma_f32_16x16x32_bf16 v[46:49], v[150:153], v[190:193], v[46:49]
	v_mfma_f32_16x16x32_bf16 v[38:41], v[158:161], v[190:193], v[38:41]
	v_mfma_f32_16x16x32_bf16 v[30:33], v[150:153], v[198:201], v[30:33]
	v_mfma_f32_16x16x32_bf16 v[22:25], v[158:161], v[198:201], v[22:25]
	v_mfma_f32_16x16x32_bf16 v[14:17], v[150:153], v[216:219], v[14:17]
	v_mfma_f32_16x16x32_bf16 v[6:9], v[158:161], v[216:219], v[6:9]
	s_setprio 0
	s_setprio 1
	v_mfma_f32_16x16x32_bf16 v[58:61], v[162:165], v[178:181], 0
	v_mfma_f32_16x16x32_bf16 v[50:53], v[170:173], v[178:181], 0
	v_mfma_f32_16x16x32_bf16 v[42:45], v[162:165], v[186:189], 0
	v_mfma_f32_16x16x32_bf16 v[34:37], v[170:173], v[186:189], 0
	v_mfma_f32_16x16x32_bf16 v[26:29], v[162:165], v[194:197], 0
	v_mfma_f32_16x16x32_bf16 v[18:21], v[170:173], v[194:197], 0
	v_mfma_f32_16x16x32_bf16 v[10:13], v[162:165], v[202:205], 0
	v_mfma_f32_16x16x32_bf16 v[2:5], v[170:173], v[202:205], 0
	v_mfma_f32_16x16x32_bf16 v[58:61], v[166:169], v[182:185], v[58:61]
	v_mfma_f32_16x16x32_bf16 v[50:53], v[174:177], v[182:185], v[50:53]
	v_mfma_f32_16x16x32_bf16 v[42:45], v[166:169], v[190:193], v[42:45]
	v_mfma_f32_16x16x32_bf16 v[34:37], v[174:177], v[190:193], v[34:37]
	v_mfma_f32_16x16x32_bf16 v[26:29], v[166:169], v[198:201], v[26:29]
	v_mfma_f32_16x16x32_bf16 v[18:21], v[174:177], v[198:201], v[18:21]
	v_mfma_f32_16x16x32_bf16 v[10:13], v[166:169], v[216:219], v[10:13]
	v_mfma_f32_16x16x32_bf16 v[2:5], v[174:177], v[216:219], v[2:5]
	s_setprio 0
	s_barrier
	s_add_i32 s70, 0, 0x18000
	s_add_i32 s76, 0, 0x1c000
	v_add_u32_e32 v158, s70, v143
	v_add_u32_e32 v174, s76, v143
	ds_read_b128 v[146:149], v158
	ds_read_b128 v[150:153], v158 offset:1024
	ds_read_b128 v[154:157], v158 offset:2048
	ds_read_b128 v[158:161], v158 offset:3072
	ds_read_b128 v[162:165], v174
	ds_read_b128 v[166:169], v174 offset:1024
	ds_read_b128 v[170:173], v174 offset:2048
	ds_read_b128 v[174:177], v174 offset:3072
	s_add_u32 s24, s24, 0x40000
	s_addc_u32 s25, s25, 0
	s_mov_b32 m0, s48
	v_lshl_add_u64 v[228:229], s[24:25], 0, v[134:135]
	ds_read_b128 v[178:181], v145 offset:32768
	ds_read_b128 v[182:185], v145 offset:33792
	ds_read_b128 v[186:189], v145 offset:34816
	ds_read_b128 v[190:193], v145 offset:35840
	ds_read_b128 v[194:197], v145 offset:36864
	ds_read_b128 v[198:201], v145 offset:37888
	ds_read_b128 v[202:205], v145 offset:38912
	ds_read_b128 v[216:219], v145 offset:39936
	global_load_lds_dwordx4 v[228:229], off
	v_lshl_add_u64 v[228:229], s[24:25], 0, v[132:133]
	s_mov_b32 m0, s49
	s_nop 0
	global_load_lds_dwordx4 v[228:229], off
	s_waitcnt vmcnt(8)
	s_waitcnt lgkmcnt(0)
	s_barrier
	s_setprio 1
	s_waitcnt lgkmcnt(0)
	v_mfma_f32_16x16x32_bf16 v[126:129], v[146:149], v[178:181], v[126:129]
	v_mfma_f32_16x16x32_bf16 v[118:121], v[154:157], v[178:181], v[118:121]
	v_mfma_f32_16x16x32_bf16 v[110:113], v[146:149], v[186:189], v[110:113]
	v_mfma_f32_16x16x32_bf16 v[102:105], v[154:157], v[186:189], v[102:105]
	v_mfma_f32_16x16x32_bf16 v[94:97], v[146:149], v[194:197], v[94:97]
	v_mfma_f32_16x16x32_bf16 v[86:89], v[154:157], v[194:197], v[86:89]
	v_mfma_f32_16x16x32_bf16 v[78:81], v[146:149], v[202:205], v[78:81]
	v_mfma_f32_16x16x32_bf16 v[70:73], v[154:157], v[202:205], v[70:73]
	v_mfma_f32_16x16x32_bf16 v[126:129], v[150:153], v[182:185], v[126:129]
	v_mfma_f32_16x16x32_bf16 v[118:121], v[158:161], v[182:185], v[118:121]
	v_mfma_f32_16x16x32_bf16 v[110:113], v[150:153], v[190:193], v[110:113]
	v_mfma_f32_16x16x32_bf16 v[102:105], v[158:161], v[190:193], v[102:105]
	v_mfma_f32_16x16x32_bf16 v[94:97], v[150:153], v[198:201], v[94:97]
	v_mfma_f32_16x16x32_bf16 v[86:89], v[158:161], v[198:201], v[86:89]
	v_mfma_f32_16x16x32_bf16 v[78:81], v[150:153], v[216:219], v[78:81]
	v_mfma_f32_16x16x32_bf16 v[70:73], v[158:161], v[216:219], v[70:73]
	s_setprio 0
	s_setprio 1
	v_mfma_f32_16x16x32_bf16 v[122:125], v[162:165], v[178:181], v[122:125]
	v_mfma_f32_16x16x32_bf16 v[114:117], v[170:173], v[178:181], v[114:117]
	v_mfma_f32_16x16x32_bf16 v[106:109], v[162:165], v[186:189], v[106:109]
	v_mfma_f32_16x16x32_bf16 v[98:101], v[170:173], v[186:189], v[98:101]
	v_mfma_f32_16x16x32_bf16 v[90:93], v[162:165], v[194:197], v[90:93]
	v_mfma_f32_16x16x32_bf16 v[82:85], v[170:173], v[194:197], v[82:85]
	v_mfma_f32_16x16x32_bf16 v[74:77], v[162:165], v[202:205], v[74:77]
	v_mfma_f32_16x16x32_bf16 v[66:69], v[170:173], v[202:205], v[66:69]
	v_mfma_f32_16x16x32_bf16 v[122:125], v[166:169], v[182:185], v[122:125]
	v_mfma_f32_16x16x32_bf16 v[114:117], v[174:177], v[182:185], v[114:117]
	v_mfma_f32_16x16x32_bf16 v[106:109], v[166:169], v[190:193], v[106:109]
	v_mfma_f32_16x16x32_bf16 v[98:101], v[174:177], v[190:193], v[98:101]
	v_mfma_f32_16x16x32_bf16 v[90:93], v[166:169], v[198:201], v[90:93]
	v_mfma_f32_16x16x32_bf16 v[82:85], v[174:177], v[198:201], v[82:85]
	v_mfma_f32_16x16x32_bf16 v[74:77], v[166:169], v[216:219], v[74:77]
	v_mfma_f32_16x16x32_bf16 v[66:69], v[174:177], v[216:219], v[66:69]
	s_setprio 0
	s_barrier
	s_add_i32 s24, s70, s12
	v_lshl_add_u64 v[140:141], v[140:141], 0, s[30:31]
	s_mov_b32 m0, s24
	ds_read_b128 v[178:181], v145 offset:49152
	ds_read_b128 v[182:185], v145 offset:50176
	ds_read_b128 v[186:189], v145 offset:51200
	ds_read_b128 v[190:193], v145 offset:52224
	ds_read_b128 v[194:197], v145 offset:53248
	ds_read_b128 v[198:201], v145 offset:54272
	ds_read_b128 v[202:205], v145 offset:55296
	ds_read_b128 v[216:219], v145 offset:56320
	global_load_lds_dwordx4 v[140:141], off
	s_add_i32 m0, s24, 0x2000
	s_add_u32 s22, s22, 0x40080
	v_lshl_add_u64 v[140:141], v[220:221], 0, s[30:31]
	s_addc_u32 s23, s23, 0
	s_add_i32 s24, s76, s12
	global_load_lds_dwordx4 v[140:141], off
	v_lshl_add_u64 v[140:141], s[22:23], 0, v[0:1]
	s_mov_b32 m0, s24
	s_nop 0
	global_load_lds_dwordx4 v[140:141], off
	v_lshl_add_u64 v[140:141], s[22:23], 0, v[130:131]
	s_add_i32 m0, s24, 0x2000
	s_nop 0
	global_load_lds_dwordx4 v[140:141], off
	v_lshl_add_u64 v[140:141], v[222:223], 0, s[30:31]
	s_mov_b32 m0, s50
	s_nop 0
	global_load_lds_dwordx4 v[140:141], off
	v_lshl_add_u64 v[140:141], v[224:225], 0, s[30:31]
	s_mov_b32 m0, s51
	s_nop 0
	global_load_lds_dwordx4 v[140:141], off
	s_waitcnt vmcnt(8)
	s_waitcnt lgkmcnt(0)
	s_barrier
	s_setprio 1
	s_waitcnt lgkmcnt(0)
	v_mfma_f32_16x16x32_bf16 v[62:65], v[146:149], v[178:181], v[62:65]
	v_mfma_f32_16x16x32_bf16 v[54:57], v[154:157], v[178:181], v[54:57]
	v_mfma_f32_16x16x32_bf16 v[46:49], v[146:149], v[186:189], v[46:49]
	v_mfma_f32_16x16x32_bf16 v[38:41], v[154:157], v[186:189], v[38:41]
	v_mfma_f32_16x16x32_bf16 v[30:33], v[146:149], v[194:197], v[30:33]
	v_mfma_f32_16x16x32_bf16 v[22:25], v[154:157], v[194:197], v[22:25]
	v_mfma_f32_16x16x32_bf16 v[14:17], v[146:149], v[202:205], v[14:17]
	v_mfma_f32_16x16x32_bf16 v[6:9], v[154:157], v[202:205], v[6:9]
	v_mfma_f32_16x16x32_bf16 v[62:65], v[150:153], v[182:185], v[62:65]
	v_mfma_f32_16x16x32_bf16 v[54:57], v[158:161], v[182:185], v[54:57]
	v_mfma_f32_16x16x32_bf16 v[46:49], v[150:153], v[190:193], v[46:49]
	v_mfma_f32_16x16x32_bf16 v[38:41], v[158:161], v[190:193], v[38:41]
	v_mfma_f32_16x16x32_bf16 v[30:33], v[150:153], v[198:201], v[30:33]
	v_mfma_f32_16x16x32_bf16 v[22:25], v[158:161], v[198:201], v[22:25]
	v_mfma_f32_16x16x32_bf16 v[14:17], v[150:153], v[216:219], v[14:17]
	v_mfma_f32_16x16x32_bf16 v[6:9], v[158:161], v[216:219], v[6:9]
	s_setprio 0
	s_setprio 1
	v_mfma_f32_16x16x32_bf16 v[58:61], v[162:165], v[178:181], v[58:61]
	v_mfma_f32_16x16x32_bf16 v[50:53], v[170:173], v[178:181], v[50:53]
	v_mfma_f32_16x16x32_bf16 v[42:45], v[162:165], v[186:189], v[42:45]
	v_mfma_f32_16x16x32_bf16 v[34:37], v[170:173], v[186:189], v[34:37]
	v_mfma_f32_16x16x32_bf16 v[26:29], v[162:165], v[194:197], v[26:29]
	v_mfma_f32_16x16x32_bf16 v[18:21], v[170:173], v[194:197], v[18:21]
	v_mfma_f32_16x16x32_bf16 v[10:13], v[162:165], v[202:205], v[10:13]
	v_mfma_f32_16x16x32_bf16 v[2:5], v[170:173], v[202:205], v[2:5]
	v_mfma_f32_16x16x32_bf16 v[58:61], v[166:169], v[182:185], v[58:61]
	v_mfma_f32_16x16x32_bf16 v[50:53], v[174:177], v[182:185], v[50:53]
	v_mfma_f32_16x16x32_bf16 v[42:45], v[166:169], v[190:193], v[42:45]
	v_mfma_f32_16x16x32_bf16 v[34:37], v[174:177], v[190:193], v[34:37]
	v_mfma_f32_16x16x32_bf16 v[26:29], v[166:169], v[198:201], v[26:29]
	v_mfma_f32_16x16x32_bf16 v[18:21], v[174:177], v[198:201], v[18:21]
	v_mfma_f32_16x16x32_bf16 v[10:13], v[166:169], v[216:219], v[10:13]
	v_mfma_f32_16x16x32_bf16 v[2:5], v[174:177], v[216:219], v[2:5]
	s_setprio 0
	s_barrier
	s_add_i32 s65, s65, 2
	s_add_u32 s20, s20, 0x100
	s_addc_u32 s21, s21, 0
	s_add_u32 s61, s61, 0x100
	s_addc_u32 s64, s64, 0
	s_cmp_gt_u32 s65, 13
	s_cbranch_scc0 .LBB0_944
	s_branch .Lgemm_kexit_3

.LBB0_1019:
	s_add_u32 s42, s18, 0x100
	s_addc_u32 s43, s19, 0
	s_mov_b32 s61, -2
	s_add_u32 s18, s14, 0x100
	s_addc_u32 s19, s15, 0
	s_add_i32 s64, 0, 0x10000
	s_cmp_eq_u32 s61, 40
	s_cselect_b32 s23, s1, s19
	s_cselect_b32 s22, s0, s18
	s_cselect_b32 s21, s11, s43
	s_cselect_b32 s20, s10, s42
	s_add_i32 s65, 0, 0x14000
	v_add_u32_e32 v148, s64, v157
	v_add_u32_e32 v168, s65, v157
	ds_read_b128 v[136:139], v148
	ds_read_b128 v[140:143], v148 offset:1024
	ds_read_b128 v[144:147], v148 offset:2048
	ds_read_b128 v[148:151], v148 offset:3072
	ds_read_b128 v[152:155], v168
	ds_read_b128 v[160:163], v168 offset:1024
	ds_read_b128 v[164:167], v168 offset:2048
	ds_read_b128 v[168:171], v168 offset:3072
	v_lshl_add_u64 v[204:205], s[14:15], 0, v[132:133]
	s_add_i32 m0, s36, 0xc000
	ds_read_b128 v[172:175], v159
	ds_read_b128 v[176:179], v159 offset:1024
	ds_read_b128 v[180:183], v159 offset:2048
	ds_read_b128 v[184:187], v159 offset:3072
	ds_read_b128 v[188:191], v159 offset:4096
	ds_read_b128 v[192:195], v159 offset:5120
	ds_read_b128 v[196:199], v159 offset:6144
	ds_read_b128 v[200:203], v159 offset:7168
	global_load_lds_dwordx4 v[204:205], off
	v_lshl_add_u64 v[204:205], s[14:15], 0, v[134:135]
	s_add_i32 m0, s36, 0xe000
	s_nop 0
	global_load_lds_dwordx4 v[204:205], off
	s_waitcnt vmcnt(8)
	s_waitcnt lgkmcnt(0)
	s_barrier
	s_setprio 1
	s_waitcnt lgkmcnt(0)
	v_mfma_f32_16x16x32_bf16 v[126:129], v[136:139], v[172:175], 0
	v_mfma_f32_16x16x32_bf16 v[122:125], v[144:147], v[172:175], 0
	v_mfma_f32_16x16x32_bf16 v[110:113], v[136:139], v[180:183], 0
	v_mfma_f32_16x16x32_bf16 v[106:109], v[144:147], v[180:183], 0
	v_mfma_f32_16x16x32_bf16 v[94:97], v[136:139], v[188:191], 0
	v_mfma_f32_16x16x32_bf16 v[90:93], v[144:147], v[188:191], 0
	v_mfma_f32_16x16x32_bf16 v[78:81], v[136:139], v[196:199], 0
	v_mfma_f32_16x16x32_bf16 v[74:77], v[144:147], v[196:199], 0
	v_mfma_f32_16x16x32_bf16 v[126:129], v[140:143], v[176:179], v[126:129]
	v_mfma_f32_16x16x32_bf16 v[122:125], v[148:151], v[176:179], v[122:125]
	v_mfma_f32_16x16x32_bf16 v[110:113], v[140:143], v[184:187], v[110:113]
	v_mfma_f32_16x16x32_bf16 v[106:109], v[148:151], v[184:187], v[106:109]
	v_mfma_f32_16x16x32_bf16 v[94:97], v[140:143], v[192:195], v[94:97]
	v_mfma_f32_16x16x32_bf16 v[90:93], v[148:151], v[192:195], v[90:93]
	v_mfma_f32_16x16x32_bf16 v[78:81], v[140:143], v[200:203], v[78:81]
	v_mfma_f32_16x16x32_bf16 v[74:77], v[148:151], v[200:203], v[74:77]
	s_setprio 0
	s_setprio 1
	v_mfma_f32_16x16x32_bf16 v[118:121], v[152:155], v[172:175], 0
	v_mfma_f32_16x16x32_bf16 v[114:117], v[164:167], v[172:175], 0
	v_mfma_f32_16x16x32_bf16 v[102:105], v[152:155], v[180:183], 0
	v_mfma_f32_16x16x32_bf16 v[98:101], v[164:167], v[180:183], 0
	v_mfma_f32_16x16x32_bf16 v[86:89], v[152:155], v[188:191], 0
	v_mfma_f32_16x16x32_bf16 v[82:85], v[164:167], v[188:191], 0
	v_mfma_f32_16x16x32_bf16 v[70:73], v[152:155], v[196:199], 0
	v_mfma_f32_16x16x32_bf16 v[66:69], v[164:167], v[196:199], 0
	v_mfma_f32_16x16x32_bf16 v[118:121], v[160:163], v[176:179], v[118:121]
	v_mfma_f32_16x16x32_bf16 v[114:117], v[168:171], v[176:179], v[114:117]
	v_mfma_f32_16x16x32_bf16 v[102:105], v[160:163], v[184:187], v[102:105]
	v_mfma_f32_16x16x32_bf16 v[98:101], v[168:171], v[184:187], v[98:101]
	v_mfma_f32_16x16x32_bf16 v[86:89], v[160:163], v[192:195], v[86:89]
	v_mfma_f32_16x16x32_bf16 v[82:85], v[168:171], v[192:195], v[82:85]
	v_mfma_f32_16x16x32_bf16 v[70:73], v[160:163], v[200:203], v[70:73]
	v_mfma_f32_16x16x32_bf16 v[66:69], v[168:171], v[200:203], v[66:69]
	s_setprio 0
	s_barrier
	s_add_i32 s14, s64, s12
	v_lshl_add_u64 v[204:205], s[20:21], 0, v[0:1]
	s_mov_b32 m0, s14
	ds_read_b128 v[172:175], v159 offset:16384
	ds_read_b128 v[176:179], v159 offset:17408
	ds_read_b128 v[180:183], v159 offset:18432
	ds_read_b128 v[184:187], v159 offset:19456
	ds_read_b128 v[188:191], v159 offset:20480
	ds_read_b128 v[192:195], v159 offset:21504
	ds_read_b128 v[196:199], v159 offset:22528
	ds_read_b128 v[200:203], v159 offset:23552
	global_load_lds_dwordx4 v[204:205], off
	s_add_i32 m0, s14, 0x2000
	s_add_u32 s14, s20, 0xb0000
	v_lshl_add_u64 v[216:217], s[20:21], 0, v[130:131]
	s_addc_u32 s15, s21, 0
	s_add_i32 s64, s65, s12
	global_load_lds_dwordx4 v[216:217], off
	v_lshl_add_u64 v[218:219], s[14:15], 0, v[0:1]
	s_mov_b32 m0, s64
	v_lshl_add_u64 v[220:221], s[22:23], 0, v[130:131]
	global_load_lds_dwordx4 v[218:219], off
	v_lshl_add_u64 v[218:219], s[14:15], 0, v[130:131]
	s_add_i32 m0, s64, 0x2000
	s_nop 0
	global_load_lds_dwordx4 v[218:219], off
	v_lshl_add_u64 v[218:219], s[22:23], 0, v[0:1]
	s_mov_b32 m0, s36
	s_nop 0
	global_load_lds_dwordx4 v[218:219], off
	s_mov_b32 m0, s37
	s_nop 0
	global_load_lds_dwordx4 v[220:221], off
	s_waitcnt vmcnt(8)
	s_waitcnt lgkmcnt(0)
	s_barrier
	s_setprio 1
	s_waitcnt lgkmcnt(0)
	v_mfma_f32_16x16x32_bf16 v[62:65], v[136:139], v[172:175], 0
	v_mfma_f32_16x16x32_bf16 v[58:61], v[144:147], v[172:175], 0
	v_mfma_f32_16x16x32_bf16 v[46:49], v[136:139], v[180:183], 0
	v_mfma_f32_16x16x32_bf16 v[42:45], v[144:147], v[180:183], 0
	v_mfma_f32_16x16x32_bf16 v[30:33], v[136:139], v[188:191], 0
	v_mfma_f32_16x16x32_bf16 v[26:29], v[144:147], v[188:191], 0
	v_mfma_f32_16x16x32_bf16 v[14:17], v[136:139], v[196:199], 0
	v_mfma_f32_16x16x32_bf16 v[10:13], v[144:147], v[196:199], 0
	v_mfma_f32_16x16x32_bf16 v[62:65], v[140:143], v[176:179], v[62:65]
	v_mfma_f32_16x16x32_bf16 v[58:61], v[148:151], v[176:179], v[58:61]
	v_mfma_f32_16x16x32_bf16 v[46:49], v[140:143], v[184:187], v[46:49]
	v_mfma_f32_16x16x32_bf16 v[42:45], v[148:151], v[184:187], v[42:45]
	v_mfma_f32_16x16x32_bf16 v[30:33], v[140:143], v[192:195], v[30:33]
	v_mfma_f32_16x16x32_bf16 v[26:29], v[148:151], v[192:195], v[26:29]
	v_mfma_f32_16x16x32_bf16 v[14:17], v[140:143], v[200:203], v[14:17]
	v_mfma_f32_16x16x32_bf16 v[10:13], v[148:151], v[200:203], v[10:13]
	s_setprio 0
	s_setprio 1
	v_mfma_f32_16x16x32_bf16 v[54:57], v[152:155], v[172:175], 0
	v_mfma_f32_16x16x32_bf16 v[50:53], v[164:167], v[172:175], 0
	v_mfma_f32_16x16x32_bf16 v[38:41], v[152:155], v[180:183], 0
	v_mfma_f32_16x16x32_bf16 v[34:37], v[164:167], v[180:183], 0
	v_mfma_f32_16x16x32_bf16 v[22:25], v[152:155], v[188:191], 0
	v_mfma_f32_16x16x32_bf16 v[18:21], v[164:167], v[188:191], 0
	v_mfma_f32_16x16x32_bf16 v[6:9], v[152:155], v[196:199], 0
	v_mfma_f32_16x16x32_bf16 v[2:5], v[164:167], v[196:199], 0
	v_mfma_f32_16x16x32_bf16 v[54:57], v[160:163], v[176:179], v[54:57]
	v_mfma_f32_16x16x32_bf16 v[50:53], v[168:171], v[176:179], v[50:53]
	v_mfma_f32_16x16x32_bf16 v[38:41], v[160:163], v[184:187], v[38:41]
	v_mfma_f32_16x16x32_bf16 v[34:37], v[168:171], v[184:187], v[34:37]
	v_mfma_f32_16x16x32_bf16 v[22:25], v[160:163], v[192:195], v[22:25]
	v_mfma_f32_16x16x32_bf16 v[18:21], v[168:171], v[192:195], v[18:21]
	v_mfma_f32_16x16x32_bf16 v[6:9], v[160:163], v[200:203], v[6:9]
	v_mfma_f32_16x16x32_bf16 v[2:5], v[168:171], v[200:203], v[2:5]
	s_setprio 0
	s_barrier
	s_add_i32 s64, 0, 0x18000
	s_add_i32 s65, 0, 0x1c000
	v_add_u32_e32 v148, s64, v157
	v_add_u32_e32 v168, s65, v157
	ds_read_b128 v[136:139], v148
	ds_read_b128 v[140:143], v148 offset:1024
	ds_read_b128 v[144:147], v148 offset:2048
	ds_read_b128 v[148:151], v148 offset:3072
	ds_read_b128 v[152:155], v168
	ds_read_b128 v[160:163], v168 offset:1024
	ds_read_b128 v[164:167], v168 offset:2048
	ds_read_b128 v[168:171], v168 offset:3072
	s_add_u32 s14, s22, 0xb0000
	s_addc_u32 s15, s23, 0
	s_mov_b32 m0, s44
	v_lshl_add_u64 v[222:223], s[14:15], 0, v[0:1]
	ds_read_b128 v[172:175], v159 offset:32768
	ds_read_b128 v[176:179], v159 offset:33792
	ds_read_b128 v[180:183], v159 offset:34816
	ds_read_b128 v[184:187], v159 offset:35840
	ds_read_b128 v[188:191], v159 offset:36864
	ds_read_b128 v[192:195], v159 offset:37888
	ds_read_b128 v[196:199], v159 offset:38912
	ds_read_b128 v[200:203], v159 offset:39936
	global_load_lds_dwordx4 v[222:223], off
	v_lshl_add_u64 v[222:223], s[14:15], 0, v[130:131]
	s_mov_b32 m0, s45
	s_nop 0
	global_load_lds_dwordx4 v[222:223], off
	s_waitcnt vmcnt(8)
	s_waitcnt lgkmcnt(0)
	s_barrier
	s_setprio 1
	s_waitcnt lgkmcnt(0)
	v_mfma_f32_16x16x32_bf16 v[126:129], v[136:139], v[172:175], v[126:129]
	v_mfma_f32_16x16x32_bf16 v[122:125], v[144:147], v[172:175], v[122:125]
	v_mfma_f32_16x16x32_bf16 v[110:113], v[136:139], v[180:183], v[110:113]
	v_mfma_f32_16x16x32_bf16 v[106:109], v[144:147], v[180:183], v[106:109]
	v_mfma_f32_16x16x32_bf16 v[94:97], v[136:139], v[188:191], v[94:97]
	v_mfma_f32_16x16x32_bf16 v[90:93], v[144:147], v[188:191], v[90:93]
	v_mfma_f32_16x16x32_bf16 v[78:81], v[136:139], v[196:199], v[78:81]
	v_mfma_f32_16x16x32_bf16 v[74:77], v[144:147], v[196:199], v[74:77]
	v_mfma_f32_16x16x32_bf16 v[126:129], v[140:143], v[176:179], v[126:129]
	v_mfma_f32_16x16x32_bf16 v[122:125], v[148:151], v[176:179], v[122:125]
	v_mfma_f32_16x16x32_bf16 v[110:113], v[140:143], v[184:187], v[110:113]
	v_mfma_f32_16x16x32_bf16 v[106:109], v[148:151], v[184:187], v[106:109]
	v_mfma_f32_16x16x32_bf16 v[94:97], v[140:143], v[192:195], v[94:97]
	v_mfma_f32_16x16x32_bf16 v[90:93], v[148:151], v[192:195], v[90:93]
	v_mfma_f32_16x16x32_bf16 v[78:81], v[140:143], v[200:203], v[78:81]
	v_mfma_f32_16x16x32_bf16 v[74:77], v[148:151], v[200:203], v[74:77]
	s_setprio 0
	s_setprio 1
	v_mfma_f32_16x16x32_bf16 v[118:121], v[152:155], v[172:175], v[118:121]
	v_mfma_f32_16x16x32_bf16 v[114:117], v[164:167], v[172:175], v[114:117]
	v_mfma_f32_16x16x32_bf16 v[102:105], v[152:155], v[180:183], v[102:105]
	v_mfma_f32_16x16x32_bf16 v[98:101], v[164:167], v[180:183], v[98:101]
	v_mfma_f32_16x16x32_bf16 v[86:89], v[152:155], v[188:191], v[86:89]
	v_mfma_f32_16x16x32_bf16 v[82:85], v[164:167], v[188:191], v[82:85]
	v_mfma_f32_16x16x32_bf16 v[70:73], v[152:155], v[196:199], v[70:73]
	v_mfma_f32_16x16x32_bf16 v[66:69], v[164:167], v[196:199], v[66:69]
	v_mfma_f32_16x16x32_bf16 v[118:121], v[160:163], v[176:179], v[118:121]
	v_mfma_f32_16x16x32_bf16 v[114:117], v[168:171], v[176:179], v[114:117]
	v_mfma_f32_16x16x32_bf16 v[102:105], v[160:163], v[184:187], v[102:105]
	v_mfma_f32_16x16x32_bf16 v[98:101], v[168:171], v[184:187], v[98:101]
	v_mfma_f32_16x16x32_bf16 v[86:89], v[160:163], v[192:195], v[86:89]
	v_mfma_f32_16x16x32_bf16 v[82:85], v[168:171], v[192:195], v[82:85]
	v_mfma_f32_16x16x32_bf16 v[70:73], v[160:163], v[200:203], v[70:73]
	v_mfma_f32_16x16x32_bf16 v[66:69], v[168:171], v[200:203], v[66:69]
	s_setprio 0
	s_barrier
	s_add_i32 s14, s64, s12
	v_lshl_add_u64 v[204:205], v[204:205], 0, s[30:31]
	s_mov_b32 m0, s14
	ds_read_b128 v[172:175], v159 offset:49152
	ds_read_b128 v[176:179], v159 offset:50176
	ds_read_b128 v[180:183], v159 offset:51200
	ds_read_b128 v[184:187], v159 offset:52224
	ds_read_b128 v[188:191], v159 offset:53248
	ds_read_b128 v[192:195], v159 offset:54272
	ds_read_b128 v[196:199], v159 offset:55296
	ds_read_b128 v[200:203], v159 offset:56320
	global_load_lds_dwordx4 v[204:205], off
	s_add_i32 m0, s14, 0x2000
	s_add_u32 s14, s20, 0xb0080
	v_lshl_add_u64 v[204:205], v[216:217], 0, s[30:31]
	s_addc_u32 s15, s21, 0
	s_add_i32 s20, s65, s12
	global_load_lds_dwordx4 v[204:205], off
	v_lshl_add_u64 v[204:205], s[14:15], 0, v[0:1]
	s_mov_b32 m0, s20
	s_nop 0
	global_load_lds_dwordx4 v[204:205], off
	v_lshl_add_u64 v[204:205], s[14:15], 0, v[130:131]
	s_add_i32 m0, s20, 0x2000
	s_nop 0
	global_load_lds_dwordx4 v[204:205], off
	v_lshl_add_u64 v[204:205], v[218:219], 0, s[30:31]
	s_mov_b32 m0, s50
	s_nop 0
	global_load_lds_dwordx4 v[204:205], off
	v_lshl_add_u64 v[204:205], v[220:221], 0, s[30:31]
	s_mov_b32 m0, s51
	s_nop 0
	global_load_lds_dwordx4 v[204:205], off
	s_waitcnt vmcnt(8)
	s_waitcnt lgkmcnt(0)
	s_barrier
	s_setprio 1
	s_waitcnt lgkmcnt(0)
	v_mfma_f32_16x16x32_bf16 v[62:65], v[136:139], v[172:175], v[62:65]
	v_mfma_f32_16x16x32_bf16 v[58:61], v[144:147], v[172:175], v[58:61]
	v_mfma_f32_16x16x32_bf16 v[46:49], v[136:139], v[180:183], v[46:49]
	v_mfma_f32_16x16x32_bf16 v[42:45], v[144:147], v[180:183], v[42:45]
	v_mfma_f32_16x16x32_bf16 v[30:33], v[136:139], v[188:191], v[30:33]
	v_mfma_f32_16x16x32_bf16 v[26:29], v[144:147], v[188:191], v[26:29]
	v_mfma_f32_16x16x32_bf16 v[14:17], v[136:139], v[196:199], v[14:17]
	v_mfma_f32_16x16x32_bf16 v[10:13], v[144:147], v[196:199], v[10:13]
	v_mfma_f32_16x16x32_bf16 v[62:65], v[140:143], v[176:179], v[62:65]
	v_mfma_f32_16x16x32_bf16 v[58:61], v[148:151], v[176:179], v[58:61]
	v_mfma_f32_16x16x32_bf16 v[46:49], v[140:143], v[184:187], v[46:49]
	v_mfma_f32_16x16x32_bf16 v[42:45], v[148:151], v[184:187], v[42:45]
	v_mfma_f32_16x16x32_bf16 v[30:33], v[140:143], v[192:195], v[30:33]
	v_mfma_f32_16x16x32_bf16 v[26:29], v[148:151], v[192:195], v[26:29]
	v_mfma_f32_16x16x32_bf16 v[14:17], v[140:143], v[200:203], v[14:17]
	v_mfma_f32_16x16x32_bf16 v[10:13], v[148:151], v[200:203], v[10:13]
	s_setprio 0
	s_setprio 1
	v_mfma_f32_16x16x32_bf16 v[54:57], v[152:155], v[172:175], v[54:57]
	v_mfma_f32_16x16x32_bf16 v[50:53], v[164:167], v[172:175], v[50:53]
	v_mfma_f32_16x16x32_bf16 v[38:41], v[152:155], v[180:183], v[38:41]
	v_mfma_f32_16x16x32_bf16 v[34:37], v[164:167], v[180:183], v[34:37]
	v_mfma_f32_16x16x32_bf16 v[22:25], v[152:155], v[188:191], v[22:25]
	v_mfma_f32_16x16x32_bf16 v[18:21], v[164:167], v[188:191], v[18:21]
	v_mfma_f32_16x16x32_bf16 v[6:9], v[152:155], v[196:199], v[6:9]
	v_mfma_f32_16x16x32_bf16 v[2:5], v[164:167], v[196:199], v[2:5]
	v_mfma_f32_16x16x32_bf16 v[54:57], v[160:163], v[176:179], v[54:57]
	v_mfma_f32_16x16x32_bf16 v[50:53], v[168:171], v[176:179], v[50:53]
	v_mfma_f32_16x16x32_bf16 v[38:41], v[160:163], v[184:187], v[38:41]
	v_mfma_f32_16x16x32_bf16 v[34:37], v[168:171], v[184:187], v[34:37]
	v_mfma_f32_16x16x32_bf16 v[22:25], v[160:163], v[192:195], v[22:25]
	v_mfma_f32_16x16x32_bf16 v[18:21], v[168:171], v[192:195], v[18:21]
	v_mfma_f32_16x16x32_bf16 v[6:9], v[160:163], v[200:203], v[6:9]
	v_mfma_f32_16x16x32_bf16 v[2:5], v[168:171], v[200:203], v[2:5]
	s_setprio 0
	s_barrier
	s_add_i32 s61, s61, 2
	s_add_u32 s42, s42, 0x100
	s_addc_u32 s43, s43, 0
	s_cmp_gt_u32 s61, 41
	s_mov_b64 s[14:15], s[18:19]
	s_cbranch_scc0 .LBB0_1020
	s_branch .Lgemm_kexit_4
